# speedup vs baseline: 1.0020x; 1.0020x over previous
; #define PG8_STAGE(bufoff, gbase, voff) do { _Pragma("unroll") for (int _i = 0; _i < 2; ++_i) \
;         __builtin_amdgcn_global_load_lds((const unsigned*)((const char*)(gbase) + (voff)[_i]), (PG8_LAS unsigned*)(lds + (bufoff) + ldsw + _i * 8192), 16, 0, 0); } while (0)
; #define PG8_WAIT_V(n) asm volatile("s_waitcnt vmcnt(" #n ")" ::: "memory")
; #define PG8_BAR __builtin_amdgcn_s_barrier()
; template <class Epi, class Sched, bool ALIGN_EPI = false, bool SP2 = false>
; __device__ __forceinline__ void gemm_phase(PG8_LAS unsigned char* lds, const Gemm g, const Sched& S, const Epi& E) {
;     ...
;     const unsigned ldsw = (unsigned)wid * 1024u;
;     const int aoff = lds_byte(wr * 64 + fr, fq * 8), boff = lds_byte(wc * 32 + fr, fq * 8);
;     ...
;     Unit cur, nxt; int ui = 0;
;     if (!S.next(0, cur)) return;
;     f32x4 acc[2][2][4][2];
; #pragma unroll
;     for (int a = 0; a < 2; ++a)
; #pragma unroll
;         for (int b = 0; b < 2; ++b)
; #pragma unroll
;             for (int m = 0; m < 4; ++m)
; #pragma unroll
;                 for (int n = 0; n < 2; ++n) acc[a][b][m][n] = (f32x4){0.f, 0.f, 0.f, 0.f};
;     bf16x8 At[4][2], B0[2][2], B1[2][2];
;     const char* cA = (const char*)g.A + (size_t)cur.pm * tstep; const char* cB = (const char*)g.Bt + (size_t)cur.pn * tstep;
;     S.a_ready(cur);
;     if constexpr (SP2) {
;         PG8_STAGE(PG8_SB(0, 0), cB, voffB); PG8_STAGE(PG8_SB(0, 1), cB + hstep, voffB); PG8_STAGE(PG8_SA(0, 0), cA, voffA); PG8_STAGE(PG8_SA(0, 1), cA + hstep, voffA);
;         if (wr == 1) PG8_BAR;
;         PG8_WAIT_V(2); PG8_BAR;
;         PG8_STAGE(PG8_SB(1, 0), cB + kstep, voffB); PG8_STAGE(PG8_SA(1, 0), cA + kstep, voffA); PG8_STAGE(PG8_SB(1, 1), cB + hstep + kstep, voffB);
;         PG8_WAIT_V(6); PG8_BAR;
.LBB0_344:
	s_and_b32 s31, s22, 3
	s_mov_b64 s[22:23], 0x80
	s_add_i32 m0, s26, 0x18000
	v_lshl_add_u64 v[6:7], v[6:7], 0, s[22:23]
	s_lshl_b32 s36, s30, 13
	s_lshl_b32 s37, s31, 12
	s_waitcnt vmcnt(2)
	s_barrier
	global_load_lds_dwordx4 v[6:7], off
	v_lshl_add_u64 v[4:5], v[4:5], 0, s[22:23]
	s_add_i32 m0, s26, 0x1a000
	s_add_i32 s46, s26, 0x8000
	s_add_i32 s47, s26, 0xa000
	global_load_lds_dwordx4 v[4:5], off
	v_lshl_add_u64 v[0:1], v[0:1], 0, s[22:23]
	s_mov_b32 m0, s46
	s_add_u32 s34, s4, 0x80080
	global_load_lds_dwordx4 v[0:1], off
	v_lshl_add_u64 v[0:1], v[2:3], 0, s[22:23]
	s_mov_b32 m0, s47
	s_addc_u32 s35, s5, 0
	global_load_lds_dwordx4 v[0:1], off
	s_add_i32 m0, s26, 0x1c000
	v_lshl_add_u64 v[0:1], s[34:35], 0, v[132:133]
	global_load_lds_dwordx4 v[0:1], off
	v_lshl_add_u64 v[0:1], s[34:35], 0, v[128:129]
	s_add_i32 m0, s26, 0x1e000
	s_cmpk_lt_u32 s7, 0x100
	global_load_lds_dwordx4 v[0:1], off
	v_bfe_u32 v1, v8, 4, 2
	v_and_b32_e32 v0, 15, v8
	v_lshlrev_b32_e32 v2, 4, v1
	v_lshl_or_b32 v148, s30, 6, v0
	v_lshl_or_b32 v0, v0, 6, v2
	v_lshlrev_b32_e32 v2, 2, v8
	v_and_b32_e32 v2, 32, v2
	v_bitop3_b32 v3, v0, s36, v2 bitop3:0xde
	v_bitop3_b32 v149, v0, s37, v2 bitop3:0xde
	v_lshlrev_b32_e32 v0, 2, v1
	v_lshl_or_b32 v150, s31, 4, v0
	v_lshlrev_b32_e32 v0, 15, v13
	v_and_b32_e32 v0, 0xffff0000, v0
	v_lshl_add_u32 v0, v12, 12, v0
	v_and_b32_e32 v1, 1, v13
	v_lshl_or_b32 v0, v1, 6, v0
	v_lshl_add_u32 v136, v14, 1, v0
	v_lshlrev_b32_e32 v0, 15, v9
	v_and_b32_e32 v0, 0xffff0000, v0
	s_waitcnt vmcnt(6)
	v_lshl_add_u32 v0, v10, 12, v0
	v_and_b32_e32 v1, 1, v9
	s_sext_i32_i16 s9, s6
	s_cselect_b64 s[34:35], -1, 0
	v_readlane_b32 s6, v244, 0
	v_lshl_or_b32 v0, v1, 6, v0
	s_add_i32 s50, 0, 0x10000
	s_add_i32 s51, 0, 0x14000
	s_ashr_i32 s48, s6, 31
	s_mov_b32 s49, s6
	v_mov_b32_e32 v137, v133
	v_lshl_add_u32 v138, v11, 1, v0
	v_mov_b32_e32 v139, v133
	v_mov_b64_e32 v[140:141], 0x2100
	v_mov_b64_e32 v[142:143], 0x20ff
	v_add_u32_e32 v151, s50, v149
	v_add_u32_e32 v153, s51, v149
	v_add_u32_e32 v154, 0, v3
	v_mov_b32_e32 v155, 0x358637bd
	s_mov_b32 s52, 0x800000
	s_movk_i32 s53, 0x2c00
	s_barrier
	v_readlane_b32 s7, v244, 1
	s_branch .LBB0_347
	s_nop 0
	s_nop 0
	s_nop 0
	s_nop 0
	s_nop 0
	s_nop 0
	s_nop 0
	s_nop 0
	s_nop 0

; __device__ __forceinline__ unsigned cvt_pk_bf16(float lo, float hi) { unsigned r; asm volatile("v_cvt_pk_bf16_f32 %0, %1, %2" : "=v"(r) : "v"(lo), "v"(hi)); return r; }
;     __device__ __forceinline__ void operator()(const f32x4 (&acc)[2][2][4][2], const Unit& u, int wr, int wc, int fr, int fq) const {
;         const int row0 = u.pm * BM + wr * 64 + fr; const int fcol0 = u.pn * 128 + wc * 16 + 4 * fq;
; #pragma unroll
;         for (int ai = 0; ai < 2; ++ai)
; #pragma unroll
;             for (int m = 0; m < 4; ++m) {
;                 const int row = row0 + ai * HALF + m * 16; const float rs = rsqrtf(sumsq[row] * inv_n + eps);
; #pragma unroll
;                 for (int bj = 0; bj < 2; ++bj) {
;                     const f32x4 g = acc[ai][bj][m][0] * rs, up = acc[ai][bj][m][1] * rs; f32x4 a;
; #pragma unroll
;                     for (int e = 0; e < 4; ++e) a[e] = g[e] * __builtin_amdgcn_rcpf(1.f + __builtin_amdgcn_exp2f(-1.4426950408889634f * g[e])) * up[e];
;                     u32x2 w; w.x = cvt_pk_bf16(a[0], a[1]); w.y = cvt_pk_bf16(a[2], a[3]);
;                     *(u32x2*)(O + (size_t)row * ldo + fcol0 + bj * 64) = w;
.LBB0_353:
	v_lshl_add_u32 v144, s8, 8, v148
	v_ashrrev_i32_e32 v145, 31, v144
	v_lshl_add_u64 v[146:147], v[144:145], 2, s[18:19]
	global_load_dword v145, v[146:147], off
	global_load_dword v249, v[146:147], off offset:64
	global_load_dword v250, v[146:147], off offset:128
	global_load_dword v251, v[146:147], off offset:192
	global_load_dword v252, v[146:147], off offset:512
	global_load_dword v253, v[146:147], off offset:576
	global_load_dword v254, v[146:147], off offset:640
	global_load_dword v255, v[146:147], off offset:704
	v_lshl_or_b32 v156, s9, 7, v150
	v_ashrrev_i32_e32 v157, 31, v156
	v_mov_b32_e32 v160, v126
	v_mov_b32_e32 v161, v122
	v_mov_b32_e32 v122, v127
	v_mov_b32_e32 v126, v116
	v_mov_b32_e32 v127, v112
	v_mov_b32_e32 v112, v117
	v_lshlrev_b64 v[116:117], 1, v[156:157]
	v_or_b32_e32 v164, 16, v144
	v_ashrrev_i32_e32 v165, 31, v164
	v_mov_b32_e32 v158, v124
	v_mov_b32_e32 v159, v120
	v_mov_b32_e32 v120, v125
	v_mov_b32_e32 v162, v118
	v_mov_b32_e32 v163, v114
	v_mov_b32_e32 v114, v119
	v_mov_b64_e32 v[124:125], s[10:11]
	v_mad_i64_i32 v[118:119], s[4:5], v144, s53, v[124:125]
	v_lshl_add_u64 v[118:119], v[118:119], 0, v[116:117]
	s_waitcnt vmcnt(0)
	v_fmamk_f32 v145, v145, 0x3a000000, v155
	v_mul_f32_e32 v156, 0x4b800000, v145
	v_cmp_gt_f32_e32 vcc, s52, v145
	s_nop 1
	v_cndmask_b32_e32 v145, v145, v156, vcc
	v_rsq_f32_e32 v145, v145
	v_lshl_add_u64 v[156:157], v[164:165], 2, s[18:19]
	v_mul_f32_e32 v165, 0x45800000, v145
	v_cndmask_b32_e32 v166, v145, v165, vcc
	v_pk_mul_f32 v[158:159], v[158:159], v[166:167] op_sel_hi:[1,0]
	v_pk_mul_f32 v[120:121], v[120:121], v[166:167] op_sel_hi:[1,0]
	v_pk_mul_f32 v[160:161], v[160:161], v[166:167] op_sel_hi:[1,0]
	v_pk_mul_f32 v[122:123], v[122:123], v[166:167] op_sel_hi:[1,0]
	v_pk_mul_f32 v[126:127], v[126:127], v[166:167] op_sel_hi:[1,0]
	v_pk_mul_f32 v[112:113], v[112:113], v[166:167] op_sel_hi:[1,0]
	v_pk_mul_f32 v[162:163], v[162:163], v[166:167] op_sel_hi:[1,0]
	v_pk_mul_f32 v[114:115], v[114:115], v[166:167] op_sel_hi:[1,0]
	v_mul_f32_e32 v145, 0xbfb8aa3b, v159
	v_mul_f32_e32 v165, 0xbfb8aa3b, v121
	v_mul_f32_e32 v166, 0xbfb8aa3b, v161
	v_mul_f32_e32 v167, 0xbfb8aa3b, v123
	v_mul_f32_e32 v168, 0xbfb8aa3b, v127
	v_mul_f32_e32 v169, 0xbfb8aa3b, v113
	v_mul_f32_e32 v170, 0xbfb8aa3b, v163
	v_mul_f32_e32 v171, 0xbfb8aa3b, v115
	v_exp_f32_e32 v145, v145
	v_exp_f32_e32 v165, v165
	v_exp_f32_e32 v166, v166
	v_exp_f32_e32 v167, v167
	v_exp_f32_e32 v168, v168
	v_exp_f32_e32 v169, v169
	v_exp_f32_e32 v170, v170
	v_exp_f32_e32 v171, v171
	v_add_f32_e32 v145, 1.0, v145
	v_add_f32_e32 v165, 1.0, v165
	v_add_f32_e32 v166, 1.0, v166
	v_add_f32_e32 v167, 1.0, v167
	v_add_f32_e32 v168, 1.0, v168
	v_add_f32_e32 v169, 1.0, v169
	v_add_f32_e32 v170, 1.0, v170
	v_add_f32_e32 v171, 1.0, v171
	v_rcp_f32_e32 v145, v145
	v_rcp_f32_e32 v165, v165
	v_rcp_f32_e32 v166, v166
	v_rcp_f32_e32 v167, v167
	v_rcp_f32_e32 v168, v168
	v_rcp_f32_e32 v169, v169
	v_rcp_f32_e32 v170, v170
	v_rcp_f32_e32 v171, v171
	v_mul_f32_e32 v145, v159, v145
	v_mul_f32_e32 v121, v121, v165
	v_mul_f32_e32 v159, v161, v166
	v_mul_f32_e32 v123, v123, v167
	v_mul_f32_e32 v127, v127, v168
	v_mul_f32_e32 v113, v113, v169
	v_mul_f32_e32 v161, v163, v170
	v_mul_f32_e32 v115, v115, v171
	v_mul_f32_e32 v145, v158, v145
	v_mul_f32_e32 v120, v120, v121
	v_mul_f32_e32 v121, v160, v159
	v_mul_f32_e32 v122, v122, v123
	v_mul_f32_e32 v123, v126, v127
	v_mul_f32_e32 v126, v112, v113
	v_cvt_pk_bf16_f32 v112, v145, v120
	v_cvt_pk_bf16_f32 v113, v121, v122
	v_mul_f32_e32 v127, v162, v161
	v_mul_f32_e32 v114, v114, v115
	global_store_dwordx2 v[118:119], v[112:113], off
	v_cvt_pk_bf16_f32 v112, v123, v126
	v_cvt_pk_bf16_f32 v113, v127, v114
	global_store_dwordx2 v[118:119], v[112:113], off offset:128
	v_mov_b32_e32 v113, v104
	v_mov_b32_e32 v104, v109
	v_mov_b32_e32 v109, v106
	v_mov_b32_e32 v106, v111
	v_mov_b32_e32 v111, v96
	v_mov_b32_e32 v96, v101
	v_mov_b32_e32 v101, v98
	v_mov_b32_e32 v98, v103
	v_mov_b32_e32 v112, v108
	v_mov_b32_e32 v108, v110
	v_mov_b32_e32 v110, v100
	v_mov_b32_e32 v100, v102
	v_or_b32_e32 v102, 32, v144
	v_mad_i64_i32 v[114:115], s[4:5], v164, s53, v[124:125]
	v_lshl_add_u64 v[114:115], v[114:115], 0, v[116:117]
	v_mov_b32_e32 v118, v249
	v_fmamk_f32 v103, v118, 0x3a000000, v155
	v_mul_f32_e32 v118, 0x4b800000, v103
	v_cmp_gt_f32_e32 vcc, s52, v103
	s_nop 1
	v_cndmask_b32_e32 v103, v103, v118, vcc
	v_rsq_f32_e32 v120, v103
	v_ashrrev_i32_e32 v103, 31, v102
	v_lshl_add_u64 v[118:119], v[102:103], 2, s[18:19]
	v_mul_f32_e32 v103, 0x45800000, v120
	v_cndmask_b32_e32 v120, v120, v103, vcc
	v_pk_mul_f32 v[112:113], v[112:113], v[120:121] op_sel_hi:[1,0]
	v_pk_mul_f32 v[104:105], v[104:105], v[120:121] op_sel_hi:[1,0]
	v_pk_mul_f32 v[108:109], v[108:109], v[120:121] op_sel_hi:[1,0]
	v_pk_mul_f32 v[106:107], v[106:107], v[120:121] op_sel_hi:[1,0]
	v_pk_mul_f32 v[96:97], v[96:97], v[120:121] op_sel_hi:[1,0]
	v_pk_mul_f32 v[110:111], v[110:111], v[120:121] op_sel_hi:[1,0]
	v_pk_mul_f32 v[100:101], v[100:101], v[120:121] op_sel_hi:[1,0]
	v_pk_mul_f32 v[98:99], v[98:99], v[120:121] op_sel_hi:[1,0]
	v_mul_f32_e32 v103, 0xbfb8aa3b, v113
	v_mul_f32_e32 v120, 0xbfb8aa3b, v105
	v_mul_f32_e32 v121, 0xbfb8aa3b, v109
	v_mul_f32_e32 v122, 0xbfb8aa3b, v107
	v_mul_f32_e32 v126, 0xbfb8aa3b, v97
	v_mul_f32_e32 v123, 0xbfb8aa3b, v111
	v_mul_f32_e32 v127, 0xbfb8aa3b, v101
	v_mul_f32_e32 v145, 0xbfb8aa3b, v99
	v_exp_f32_e32 v103, v103
	v_exp_f32_e32 v120, v120
	v_exp_f32_e32 v121, v121
	v_exp_f32_e32 v122, v122
	v_exp_f32_e32 v126, v126
	v_exp_f32_e32 v123, v123
	v_exp_f32_e32 v127, v127
	v_exp_f32_e32 v145, v145
	v_add_f32_e32 v103, 1.0, v103
; __device__ __forceinline__ unsigned cvt_pk_bf16(float lo, float hi) { unsigned r; asm volatile("v_cvt_pk_bf16_f32 %0, %1, %2" : "=v"(r) : "v"(lo), "v"(hi)); return r; }
;     __device__ __forceinline__ void operator()(const f32x4 (&acc)[2][2][4][2], const Unit& u, int wr, int wc, int fr, int fq) const {
;     ...
;                 const int row = row0 + ai * HALF + m * 16; const float rs = rsqrtf(sumsq[row] * inv_n + eps);
; #pragma unroll
;                 for (int bj = 0; bj < 2; ++bj) {
;                     const f32x4 g = acc[ai][bj][m][0] * rs, up = acc[ai][bj][m][1] * rs; f32x4 a;
; #pragma unroll
;                     for (int e = 0; e < 4; ++e) a[e] = g[e] * __builtin_amdgcn_rcpf(1.f + __builtin_amdgcn_exp2f(-1.4426950408889634f * g[e])) * up[e];
;                     u32x2 w; w.x = cvt_pk_bf16(a[0], a[1]); w.y = cvt_pk_bf16(a[2], a[3]);
;                     *(u32x2*)(O + (size_t)row * ldo + fcol0 + bj * 64) = w;
	v_add_f32_e32 v120, 1.0, v120
	v_add_f32_e32 v121, 1.0, v121
	v_add_f32_e32 v122, 1.0, v122
	v_add_f32_e32 v126, 1.0, v126
	v_add_f32_e32 v123, 1.0, v123
	v_add_f32_e32 v127, 1.0, v127
	v_add_f32_e32 v145, 1.0, v145
	v_rcp_f32_e32 v103, v103
	v_rcp_f32_e32 v120, v120
	v_rcp_f32_e32 v121, v121
	v_rcp_f32_e32 v122, v122
	v_rcp_f32_e32 v126, v126
	v_rcp_f32_e32 v123, v123
	v_rcp_f32_e32 v127, v127
	v_rcp_f32_e32 v145, v145
	v_mul_f32_e32 v103, v113, v103
	v_mul_f32_e32 v105, v105, v120
	v_mul_f32_e32 v109, v109, v121
	v_mul_f32_e32 v107, v107, v122
	v_mul_f32_e32 v97, v97, v126
	v_mul_f32_e32 v111, v111, v123
	v_mul_f32_e32 v101, v101, v127
	v_mul_f32_e32 v99, v99, v145
	v_mul_f32_e32 v103, v112, v103
	v_mul_f32_e32 v104, v104, v105
	v_mul_f32_e32 v105, v108, v109
	v_mul_f32_e32 v106, v106, v107
	v_mul_f32_e32 v108, v96, v97
	v_cvt_pk_bf16_f32 v96, v103, v104
	v_cvt_pk_bf16_f32 v97, v105, v106
	v_mul_f32_e32 v107, v110, v111
	v_mul_f32_e32 v100, v100, v101
	v_mul_f32_e32 v98, v98, v99
	global_store_dwordx2 v[114:115], v[96:97], off
	v_cvt_pk_bf16_f32 v96, v107, v108
	v_cvt_pk_bf16_f32 v97, v100, v98
	global_store_dwordx2 v[114:115], v[96:97], off offset:128
	v_mov_b32_e32 v97, v88
	v_mov_b32_e32 v88, v93
	v_mov_b32_e32 v93, v90
	v_mov_b32_e32 v90, v95
	v_mov_b32_e32 v95, v80
	v_mov_b32_e32 v80, v85
	v_mov_b32_e32 v85, v82
	v_mov_b32_e32 v82, v87
	v_mad_i64_i32 v[98:99], s[4:5], v102, s53, v[124:125]
	v_mov_b32_e32 v96, v92
	v_mov_b32_e32 v92, v94
	v_mov_b32_e32 v94, v84
	v_mov_b32_e32 v84, v86
	v_or_b32_e32 v86, 48, v144
	v_lshl_add_u64 v[98:99], v[98:99], 0, v[116:117]
	v_mov_b32_e32 v100, v250
	v_fmamk_f32 v87, v100, 0x3a000000, v155
	v_mul_f32_e32 v100, 0x4b800000, v87
	v_cmp_gt_f32_e32 vcc, s52, v87
	s_nop 1
	v_cndmask_b32_e32 v87, v87, v100, vcc
	v_rsq_f32_e32 v102, v87
	v_ashrrev_i32_e32 v87, 31, v86
	v_lshl_add_u64 v[100:101], v[86:87], 2, s[18:19]
	v_mul_f32_e32 v87, 0x45800000, v102
	v_cndmask_b32_e32 v102, v102, v87, vcc
	v_pk_mul_f32 v[96:97], v[96:97], v[102:103] op_sel_hi:[1,0]
	v_pk_mul_f32 v[88:89], v[88:89], v[102:103] op_sel_hi:[1,0]
	v_pk_mul_f32 v[92:93], v[92:93], v[102:103] op_sel_hi:[1,0]
	v_pk_mul_f32 v[90:91], v[90:91], v[102:103] op_sel_hi:[1,0]
	v_pk_mul_f32 v[80:81], v[80:81], v[102:103] op_sel_hi:[1,0]
	v_pk_mul_f32 v[94:95], v[94:95], v[102:103] op_sel_hi:[1,0]
	v_pk_mul_f32 v[84:85], v[84:85], v[102:103] op_sel_hi:[1,0]
	v_pk_mul_f32 v[82:83], v[82:83], v[102:103] op_sel_hi:[1,0]
	v_mul_f32_e32 v87, 0xbfb8aa3b, v97
	v_mul_f32_e32 v102, 0xbfb8aa3b, v89
	v_mul_f32_e32 v103, 0xbfb8aa3b, v93
	v_mul_f32_e32 v104, 0xbfb8aa3b, v91
	v_mul_f32_e32 v106, 0xbfb8aa3b, v81
	v_mul_f32_e32 v105, 0xbfb8aa3b, v95
	v_mul_f32_e32 v107, 0xbfb8aa3b, v85
	v_mul_f32_e32 v108, 0xbfb8aa3b, v83
	v_exp_f32_e32 v87, v87
	v_exp_f32_e32 v102, v102
	v_exp_f32_e32 v103, v103
	v_exp_f32_e32 v104, v104
	v_exp_f32_e32 v106, v106
	v_exp_f32_e32 v105, v105
	v_exp_f32_e32 v107, v107
	v_exp_f32_e32 v108, v108
	v_add_f32_e32 v87, 1.0, v87
	v_add_f32_e32 v102, 1.0, v102
	v_add_f32_e32 v103, 1.0, v103
	v_add_f32_e32 v104, 1.0, v104
	v_add_f32_e32 v106, 1.0, v106
	v_add_f32_e32 v105, 1.0, v105
	v_add_f32_e32 v107, 1.0, v107
	v_add_f32_e32 v108, 1.0, v108
	v_rcp_f32_e32 v87, v87
	v_rcp_f32_e32 v102, v102
	v_rcp_f32_e32 v103, v103
	v_rcp_f32_e32 v104, v104
	v_rcp_f32_e32 v106, v106
	v_rcp_f32_e32 v105, v105
	v_rcp_f32_e32 v107, v107
	v_rcp_f32_e32 v108, v108
	v_mul_f32_e32 v87, v97, v87
	v_mul_f32_e32 v89, v89, v102
	v_mul_f32_e32 v93, v93, v103
	v_mul_f32_e32 v91, v91, v104
	v_mul_f32_e32 v81, v81, v106
	v_mul_f32_e32 v95, v95, v105
	v_mul_f32_e32 v85, v85, v107
	v_mul_f32_e32 v83, v83, v108
	v_mul_f32_e32 v87, v96, v87
	v_mul_f32_e32 v88, v88, v89
	v_mul_f32_e32 v89, v92, v93
	v_mul_f32_e32 v90, v90, v91
	v_mul_f32_e32 v92, v80, v81
	v_cvt_pk_bf16_f32 v80, v87, v88
	v_cvt_pk_bf16_f32 v81, v89, v90
	v_mul_f32_e32 v91, v94, v95
	v_mul_f32_e32 v84, v84, v85
	v_mul_f32_e32 v82, v82, v83
	global_store_dwordx2 v[98:99], v[80:81], off
	v_cvt_pk_bf16_f32 v80, v91, v92
	v_cvt_pk_bf16_f32 v81, v84, v82
	global_store_dwordx2 v[98:99], v[80:81], off offset:128
	v_mov_b32_e32 v80, v76
	v_mov_b32_e32 v76, v78
	v_mov_b32_e32 v78, v68
	v_mov_b32_e32 v68, v70
	v_mov_b32_e32 v81, v72
	v_mov_b32_e32 v72, v77
	v_mov_b32_e32 v77, v74
	v_mov_b32_e32 v74, v79
	v_mov_b32_e32 v79, v64
	v_mov_b32_e32 v64, v69
	v_mov_b32_e32 v69, v66
	v_mov_b32_e32 v66, v71
	v_mov_b32_e32 v82, v251
	v_fmamk_f32 v70, v82, 0x3a000000, v155
	v_mul_f32_e32 v71, 0x4b800000, v70
	v_cmp_gt_f32_e32 vcc, s52, v70
	s_nop 1
	v_cndmask_b32_e32 v70, v70, v71, vcc
	v_rsq_f32_e32 v82, v70
	v_mad_i64_i32 v[70:71], s[4:5], v86, s53, v[124:125]
	v_lshl_add_u64 v[70:71], v[70:71], 0, v[116:117]
	v_mul_f32_e32 v83, 0x45800000, v82
	v_cndmask_b32_e32 v82, v82, v83, vcc
	v_pk_mul_f32 v[80:81], v[80:81], v[82:83] op_sel_hi:[1,0]
	v_pk_mul_f32 v[72:73], v[72:73], v[82:83] op_sel_hi:[1,0]
	v_pk_mul_f32 v[76:77], v[76:77], v[82:83] op_sel_hi:[1,0]
	v_pk_mul_f32 v[74:75], v[74:75], v[82:83] op_sel_hi:[1,0]
	v_pk_mul_f32 v[64:65], v[64:65], v[82:83] op_sel_hi:[1,0]
	v_pk_mul_f32 v[78:79], v[78:79], v[82:83] op_sel_hi:[1,0]
	v_pk_mul_f32 v[68:69], v[68:69], v[82:83] op_sel_hi:[1,0]
	v_pk_mul_f32 v[66:67], v[66:67], v[82:83] op_sel_hi:[1,0]
	v_mul_f32_e32 v82, 0xbfb8aa3b, v81
	v_mul_f32_e32 v83, 0xbfb8aa3b, v73
	v_mul_f32_e32 v84, 0xbfb8aa3b, v77
	v_mul_f32_e32 v85, 0xbfb8aa3b, v75
	v_mul_f32_e32 v87, 0xbfb8aa3b, v65
	v_mul_f32_e32 v86, 0xbfb8aa3b, v79
	v_mul_f32_e32 v88, 0xbfb8aa3b, v69
	v_mul_f32_e32 v89, 0xbfb8aa3b, v67
	v_exp_f32_e32 v82, v82
	v_exp_f32_e32 v83, v83
	v_exp_f32_e32 v84, v84
	v_exp_f32_e32 v85, v85
; __device__ __forceinline__ unsigned cvt_pk_bf16(float lo, float hi) { unsigned r; asm volatile("v_cvt_pk_bf16_f32 %0, %1, %2" : "=v"(r) : "v"(lo), "v"(hi)); return r; }
;     __device__ __forceinline__ void operator()(const f32x4 (&acc)[2][2][4][2], const Unit& u, int wr, int wc, int fr, int fq) const {
;     ...
;                 const int row = row0 + ai * HALF + m * 16; const float rs = rsqrtf(sumsq[row] * inv_n + eps);
; #pragma unroll
;                 for (int bj = 0; bj < 2; ++bj) {
;                     const f32x4 g = acc[ai][bj][m][0] * rs, up = acc[ai][bj][m][1] * rs; f32x4 a;
; #pragma unroll
;                     for (int e = 0; e < 4; ++e) a[e] = g[e] * __builtin_amdgcn_rcpf(1.f + __builtin_amdgcn_exp2f(-1.4426950408889634f * g[e])) * up[e];
;                     u32x2 w; w.x = cvt_pk_bf16(a[0], a[1]); w.y = cvt_pk_bf16(a[2], a[3]);
;                     *(u32x2*)(O + (size_t)row * ldo + fcol0 + bj * 64) = w;
	v_exp_f32_e32 v87, v87
	v_exp_f32_e32 v86, v86
	v_exp_f32_e32 v88, v88
	v_exp_f32_e32 v89, v89
	v_add_f32_e32 v82, 1.0, v82
	v_add_f32_e32 v83, 1.0, v83
	v_add_f32_e32 v84, 1.0, v84
	v_add_f32_e32 v85, 1.0, v85
	v_add_f32_e32 v87, 1.0, v87
	v_add_f32_e32 v86, 1.0, v86
	v_add_f32_e32 v88, 1.0, v88
	v_add_f32_e32 v89, 1.0, v89
	v_rcp_f32_e32 v82, v82
	v_rcp_f32_e32 v83, v83
	v_rcp_f32_e32 v84, v84
	v_rcp_f32_e32 v85, v85
	v_rcp_f32_e32 v87, v87
	v_rcp_f32_e32 v86, v86
	v_rcp_f32_e32 v88, v88
	v_rcp_f32_e32 v89, v89
	v_mul_f32_e32 v81, v81, v82
	v_mul_f32_e32 v73, v73, v83
	v_mul_f32_e32 v77, v77, v84
	v_mul_f32_e32 v75, v75, v85
	v_mul_f32_e32 v65, v65, v87
	v_mul_f32_e32 v79, v79, v86
	v_mul_f32_e32 v69, v69, v88
	v_mul_f32_e32 v67, v67, v89
	v_mul_f32_e32 v80, v80, v81
	v_mul_f32_e32 v72, v72, v73
	v_mul_f32_e32 v73, v76, v77
	v_mul_f32_e32 v74, v74, v75
	v_mul_f32_e32 v76, v64, v65
	v_cvt_pk_bf16_f32 v64, v80, v72
	v_cvt_pk_bf16_f32 v65, v73, v74
	v_mul_f32_e32 v75, v78, v79
	v_mul_f32_e32 v68, v68, v69
	v_mul_f32_e32 v66, v66, v67
	global_store_dwordx2 v[70:71], v[64:65], off
	v_cvt_pk_bf16_f32 v64, v75, v76
	v_cvt_pk_bf16_f32 v65, v68, v66
	global_store_dwordx2 v[70:71], v[64:65], off offset:128
	v_mov_b32_e32 v65, v56
	v_mov_b32_e32 v56, v61
	v_mov_b32_e32 v61, v58
	v_mov_b32_e32 v58, v63
	v_mov_b32_e32 v63, v48
	v_mov_b32_e32 v48, v53
	v_mov_b32_e32 v53, v50
	v_mov_b32_e32 v50, v55
	v_mov_b32_e32 v64, v60
	v_mov_b32_e32 v60, v62
	v_mov_b32_e32 v62, v52
	v_mov_b32_e32 v52, v54
	v_add_u32_e32 v54, 0x80, v144
	v_mov_b32_e32 v66, v252
	v_fmamk_f32 v55, v66, 0x3a000000, v155
	v_mul_f32_e32 v66, 0x4b800000, v55
	v_cmp_gt_f32_e32 vcc, s52, v55
	s_nop 1
	v_cndmask_b32_e32 v55, v55, v66, vcc
	v_rsq_f32_e32 v66, v55
	v_mad_i64_i32 v[54:55], s[4:5], v54, s53, v[124:125]
	v_lshl_add_u64 v[54:55], v[54:55], 0, v[116:117]
	v_mul_f32_e32 v67, 0x45800000, v66
	v_cndmask_b32_e32 v66, v66, v67, vcc
	v_pk_mul_f32 v[64:65], v[64:65], v[66:67] op_sel_hi:[1,0]
	v_pk_mul_f32 v[56:57], v[56:57], v[66:67] op_sel_hi:[1,0]
	v_pk_mul_f32 v[60:61], v[60:61], v[66:67] op_sel_hi:[1,0]
	v_pk_mul_f32 v[58:59], v[58:59], v[66:67] op_sel_hi:[1,0]
	v_pk_mul_f32 v[48:49], v[48:49], v[66:67] op_sel_hi:[1,0]
	v_pk_mul_f32 v[62:63], v[62:63], v[66:67] op_sel_hi:[1,0]
	v_pk_mul_f32 v[52:53], v[52:53], v[66:67] op_sel_hi:[1,0]
	v_pk_mul_f32 v[50:51], v[50:51], v[66:67] op_sel_hi:[1,0]
	v_mul_f32_e32 v66, 0xbfb8aa3b, v65
	v_mul_f32_e32 v67, 0xbfb8aa3b, v57
	v_mul_f32_e32 v68, 0xbfb8aa3b, v61
	v_mul_f32_e32 v69, 0xbfb8aa3b, v59
	v_mul_f32_e32 v71, 0xbfb8aa3b, v49
	v_mul_f32_e32 v70, 0xbfb8aa3b, v63
	v_mul_f32_e32 v72, 0xbfb8aa3b, v53
	v_mul_f32_e32 v73, 0xbfb8aa3b, v51
	v_exp_f32_e32 v66, v66
	v_exp_f32_e32 v67, v67
	v_exp_f32_e32 v68, v68
	v_exp_f32_e32 v69, v69
	v_exp_f32_e32 v71, v71
	v_exp_f32_e32 v70, v70
	v_exp_f32_e32 v72, v72
	v_exp_f32_e32 v73, v73
	v_add_f32_e32 v66, 1.0, v66
	v_add_f32_e32 v67, 1.0, v67
	v_add_f32_e32 v68, 1.0, v68
	v_add_f32_e32 v69, 1.0, v69
	v_add_f32_e32 v71, 1.0, v71
	v_add_f32_e32 v70, 1.0, v70
	v_add_f32_e32 v72, 1.0, v72
	v_add_f32_e32 v73, 1.0, v73
	v_rcp_f32_e32 v66, v66
	v_rcp_f32_e32 v67, v67
	v_rcp_f32_e32 v68, v68
	v_rcp_f32_e32 v69, v69
	v_rcp_f32_e32 v71, v71
	v_rcp_f32_e32 v70, v70
	v_rcp_f32_e32 v72, v72
	v_rcp_f32_e32 v73, v73
	v_mul_f32_e32 v65, v65, v66
	v_mul_f32_e32 v57, v57, v67
	v_mul_f32_e32 v61, v61, v68
	v_mul_f32_e32 v59, v59, v69
	v_mul_f32_e32 v49, v49, v71
	v_mul_f32_e32 v63, v63, v70
	v_mul_f32_e32 v53, v53, v72
	v_mul_f32_e32 v51, v51, v73
	v_mul_f32_e32 v64, v64, v65
	v_mul_f32_e32 v56, v56, v57
	v_mul_f32_e32 v57, v60, v61
	v_mul_f32_e32 v58, v58, v59
	v_mul_f32_e32 v60, v48, v49
	v_cvt_pk_bf16_f32 v48, v64, v56
	v_cvt_pk_bf16_f32 v49, v57, v58
	v_mul_f32_e32 v59, v62, v63
	v_mul_f32_e32 v52, v52, v53
	v_mul_f32_e32 v50, v50, v51
	global_store_dwordx2 v[54:55], v[48:49], off
	v_cvt_pk_bf16_f32 v48, v59, v60
	v_cvt_pk_bf16_f32 v49, v52, v50
	global_store_dwordx2 v[54:55], v[48:49], off offset:128
	v_mov_b32_e32 v49, v40
	v_mov_b32_e32 v40, v45
	v_mov_b32_e32 v45, v42
	v_mov_b32_e32 v42, v47
	v_mov_b32_e32 v47, v32
	v_mov_b32_e32 v32, v37
	v_mov_b32_e32 v37, v34
	v_mov_b32_e32 v34, v39
	v_mov_b32_e32 v48, v44
	v_mov_b32_e32 v44, v46
	v_mov_b32_e32 v46, v36
	v_mov_b32_e32 v36, v38
	v_add_u32_e32 v38, 0x90, v144
	v_mov_b32_e32 v50, v253
	v_fmamk_f32 v39, v50, 0x3a000000, v155
	v_mul_f32_e32 v50, 0x4b800000, v39
	v_cmp_gt_f32_e32 vcc, s52, v39
	s_nop 1
	v_cndmask_b32_e32 v39, v39, v50, vcc
	v_rsq_f32_e32 v50, v39
	v_mad_i64_i32 v[38:39], s[4:5], v38, s53, v[124:125]
	v_lshl_add_u64 v[38:39], v[38:39], 0, v[116:117]
	v_mul_f32_e32 v51, 0x45800000, v50
	v_cndmask_b32_e32 v50, v50, v51, vcc
	v_pk_mul_f32 v[48:49], v[48:49], v[50:51] op_sel_hi:[1,0]
	v_pk_mul_f32 v[40:41], v[40:41], v[50:51] op_sel_hi:[1,0]
	v_pk_mul_f32 v[44:45], v[44:45], v[50:51] op_sel_hi:[1,0]
	v_pk_mul_f32 v[42:43], v[42:43], v[50:51] op_sel_hi:[1,0]
	v_pk_mul_f32 v[32:33], v[32:33], v[50:51] op_sel_hi:[1,0]
	v_pk_mul_f32 v[46:47], v[46:47], v[50:51] op_sel_hi:[1,0]
	v_pk_mul_f32 v[36:37], v[36:37], v[50:51] op_sel_hi:[1,0]
	v_pk_mul_f32 v[34:35], v[34:35], v[50:51] op_sel_hi:[1,0]
	v_mul_f32_e32 v50, 0xbfb8aa3b, v49
	v_mul_f32_e32 v51, 0xbfb8aa3b, v41
	v_mul_f32_e32 v52, 0xbfb8aa3b, v45
	v_mul_f32_e32 v53, 0xbfb8aa3b, v43
	v_mul_f32_e32 v55, 0xbfb8aa3b, v33
	v_mul_f32_e32 v54, 0xbfb8aa3b, v47
	v_mul_f32_e32 v56, 0xbfb8aa3b, v37
	v_mul_f32_e32 v57, 0xbfb8aa3b, v35
	v_exp_f32_e32 v50, v50
	v_exp_f32_e32 v51, v51
	v_exp_f32_e32 v52, v52
	v_exp_f32_e32 v53, v53
	v_exp_f32_e32 v55, v55
	v_exp_f32_e32 v54, v54
	v_exp_f32_e32 v56, v56
	v_exp_f32_e32 v57, v57
; __device__ __forceinline__ unsigned cvt_pk_bf16(float lo, float hi) { unsigned r; asm volatile("v_cvt_pk_bf16_f32 %0, %1, %2" : "=v"(r) : "v"(lo), "v"(hi)); return r; }
; #define PG8_BAR __builtin_amdgcn_s_barrier()
;     __device__ __forceinline__ void operator()(const f32x4 (&acc)[2][2][4][2], const Unit& u, int wr, int wc, int fr, int fq) const {
;     ...
;                 const int row = row0 + ai * HALF + m * 16; const float rs = rsqrtf(sumsq[row] * inv_n + eps);
; #pragma unroll
;                 for (int bj = 0; bj < 2; ++bj) {
;                     const f32x4 g = acc[ai][bj][m][0] * rs, up = acc[ai][bj][m][1] * rs; f32x4 a;
; #pragma unroll
;                     for (int e = 0; e < 4; ++e) a[e] = g[e] * __builtin_amdgcn_rcpf(1.f + __builtin_amdgcn_exp2f(-1.4426950408889634f * g[e])) * up[e];
;                     u32x2 w; w.x = cvt_pk_bf16(a[0], a[1]); w.y = cvt_pk_bf16(a[2], a[3]);
;                     *(u32x2*)(O + (size_t)row * ldo + fcol0 + bj * 64) = w;
; template <class Epi, class Sched, bool ALIGN_EPI = false, bool SP2 = false>
; __device__ __forceinline__ void gemm_phase(PG8_LAS unsigned char* lds, const Gemm g, const Sched& S, const Epi& E) {
;     ...
;         if constexpr (ALIGN_EPI) { if (wr == 0) PG8_BAR; }
;         if constexpr (!Epi::AFTER_DRAIN) { E(acc, cur, wr, wc, fr, fq); S.done(cur); }
;         if (!has_next) break;
; #pragma unroll
;         for (int a = 0; a < 2; ++a)
; #pragma unroll
;             for (int b = 0; b < 2; ++b)
; #pragma unroll
;                 for (int m = 0; m < 4; ++m)
; #pragma unroll
;                     for (int n = 0; n < 2; ++n) acc[a][b][m][n] = (f32x4){0.f, 0.f, 0.f, 0.f};
;         cur = nxt; cA = nA; cB = nB; ++ui;
;         if constexpr (ALIGN_EPI) { if (wr == 1) PG8_BAR; }
	v_add_f32_e32 v50, 1.0, v50
	v_add_f32_e32 v51, 1.0, v51
	v_add_f32_e32 v52, 1.0, v52
	v_add_f32_e32 v53, 1.0, v53
	v_add_f32_e32 v55, 1.0, v55
	v_add_f32_e32 v54, 1.0, v54
	v_add_f32_e32 v56, 1.0, v56
	v_add_f32_e32 v57, 1.0, v57
	v_rcp_f32_e32 v50, v50
	v_rcp_f32_e32 v51, v51
	v_rcp_f32_e32 v52, v52
	v_rcp_f32_e32 v53, v53
	v_rcp_f32_e32 v55, v55
	v_rcp_f32_e32 v54, v54
	v_rcp_f32_e32 v56, v56
	v_rcp_f32_e32 v57, v57
	v_mul_f32_e32 v49, v49, v50
	v_mul_f32_e32 v41, v41, v51
	v_mul_f32_e32 v45, v45, v52
	v_mul_f32_e32 v43, v43, v53
	v_mul_f32_e32 v33, v33, v55
	v_mul_f32_e32 v47, v47, v54
	v_mul_f32_e32 v37, v37, v56
	v_mul_f32_e32 v35, v35, v57
	v_mul_f32_e32 v48, v48, v49
	v_mul_f32_e32 v40, v40, v41
	v_mul_f32_e32 v41, v44, v45
	v_mul_f32_e32 v42, v42, v43
	v_mul_f32_e32 v44, v32, v33
	v_cvt_pk_bf16_f32 v32, v48, v40
	v_cvt_pk_bf16_f32 v33, v41, v42
	v_mul_f32_e32 v43, v46, v47
	v_mul_f32_e32 v36, v36, v37
	v_mul_f32_e32 v34, v34, v35
	global_store_dwordx2 v[38:39], v[32:33], off
	v_cvt_pk_bf16_f32 v32, v43, v44
	v_cvt_pk_bf16_f32 v33, v36, v34
	global_store_dwordx2 v[38:39], v[32:33], off offset:128
	v_mov_b32_e32 v33, v24
	v_mov_b32_e32 v24, v29
	v_mov_b32_e32 v29, v26
	v_mov_b32_e32 v26, v31
	v_mov_b32_e32 v31, v16
	v_mov_b32_e32 v16, v21
	v_mov_b32_e32 v21, v18
	v_mov_b32_e32 v18, v23
	v_mov_b32_e32 v32, v28
	v_mov_b32_e32 v28, v30
	v_mov_b32_e32 v30, v20
	v_mov_b32_e32 v20, v22
	v_add_u32_e32 v22, 0xa0, v144
	v_mov_b32_e32 v34, v254
	v_fmamk_f32 v23, v34, 0x3a000000, v155
	v_mul_f32_e32 v34, 0x4b800000, v23
	v_cmp_gt_f32_e32 vcc, s52, v23
	s_nop 1
	v_cndmask_b32_e32 v23, v23, v34, vcc
	v_rsq_f32_e32 v34, v23
	v_mad_i64_i32 v[22:23], s[4:5], v22, s53, v[124:125]
	v_lshl_add_u64 v[22:23], v[22:23], 0, v[116:117]
	v_mul_f32_e32 v35, 0x45800000, v34
	v_cndmask_b32_e32 v34, v34, v35, vcc
	v_pk_mul_f32 v[32:33], v[32:33], v[34:35] op_sel_hi:[1,0]
	v_pk_mul_f32 v[24:25], v[24:25], v[34:35] op_sel_hi:[1,0]
	v_pk_mul_f32 v[28:29], v[28:29], v[34:35] op_sel_hi:[1,0]
	v_pk_mul_f32 v[26:27], v[26:27], v[34:35] op_sel_hi:[1,0]
	v_pk_mul_f32 v[16:17], v[16:17], v[34:35] op_sel_hi:[1,0]
	v_pk_mul_f32 v[30:31], v[30:31], v[34:35] op_sel_hi:[1,0]
	v_pk_mul_f32 v[20:21], v[20:21], v[34:35] op_sel_hi:[1,0]
	v_pk_mul_f32 v[18:19], v[18:19], v[34:35] op_sel_hi:[1,0]
	v_mul_f32_e32 v34, 0xbfb8aa3b, v33
	v_mul_f32_e32 v35, 0xbfb8aa3b, v25
	v_mul_f32_e32 v36, 0xbfb8aa3b, v29
	v_mul_f32_e32 v37, 0xbfb8aa3b, v27
	v_mul_f32_e32 v39, 0xbfb8aa3b, v17
	v_mul_f32_e32 v38, 0xbfb8aa3b, v31
	v_mul_f32_e32 v40, 0xbfb8aa3b, v21
	v_mul_f32_e32 v41, 0xbfb8aa3b, v19
	v_exp_f32_e32 v34, v34
	v_exp_f32_e32 v35, v35
	v_exp_f32_e32 v36, v36
	v_exp_f32_e32 v37, v37
	v_exp_f32_e32 v39, v39
	v_exp_f32_e32 v38, v38
	v_exp_f32_e32 v40, v40
	v_exp_f32_e32 v41, v41
	v_add_f32_e32 v34, 1.0, v34
	v_add_f32_e32 v35, 1.0, v35
	v_add_f32_e32 v36, 1.0, v36
	v_add_f32_e32 v37, 1.0, v37
	v_add_f32_e32 v39, 1.0, v39
	v_add_f32_e32 v38, 1.0, v38
	v_add_f32_e32 v40, 1.0, v40
	v_add_f32_e32 v41, 1.0, v41
	v_rcp_f32_e32 v34, v34
	v_rcp_f32_e32 v35, v35
	v_rcp_f32_e32 v36, v36
	v_rcp_f32_e32 v37, v37
	v_rcp_f32_e32 v39, v39
	v_rcp_f32_e32 v38, v38
	v_rcp_f32_e32 v40, v40
	v_rcp_f32_e32 v41, v41
	v_mul_f32_e32 v33, v33, v34
	v_mul_f32_e32 v25, v25, v35
	v_mul_f32_e32 v29, v29, v36
	v_mul_f32_e32 v27, v27, v37
	v_mul_f32_e32 v17, v17, v39
	v_mul_f32_e32 v31, v31, v38
	v_mul_f32_e32 v21, v21, v40
	v_mul_f32_e32 v19, v19, v41
	v_mul_f32_e32 v32, v32, v33
	v_mul_f32_e32 v24, v24, v25
	v_mul_f32_e32 v25, v28, v29
	v_mul_f32_e32 v26, v26, v27
	v_mul_f32_e32 v28, v16, v17
	v_cvt_pk_bf16_f32 v16, v32, v24
	v_cvt_pk_bf16_f32 v17, v25, v26
	v_mul_f32_e32 v27, v30, v31
	v_mul_f32_e32 v20, v20, v21
	v_mul_f32_e32 v18, v18, v19
	global_store_dwordx2 v[22:23], v[16:17], off
	v_cvt_pk_bf16_f32 v16, v27, v28
	v_cvt_pk_bf16_f32 v17, v20, v18
	global_store_dwordx2 v[22:23], v[16:17], off offset:128
	v_mov_b32_e32 v17, v8
	v_mov_b32_e32 v8, v13
	v_mov_b32_e32 v13, v10
	v_mov_b32_e32 v10, v15
	v_mov_b32_e32 v15, v0
	v_mov_b32_e32 v0, v5
	v_mov_b32_e32 v5, v2
	v_mov_b32_e32 v2, v7
	v_mov_b32_e32 v16, v12
	v_mov_b32_e32 v12, v14
	v_mov_b32_e32 v14, v4
	v_mov_b32_e32 v4, v6
	v_add_u32_e32 v6, 0xb0, v144
	s_andn2_b64 vcc, exec, s[6:7]
	v_mov_b32_e32 v18, v255
	v_fmamk_f32 v7, v18, 0x3a000000, v155
	v_mul_f32_e32 v18, 0x4b800000, v7
	v_cmp_gt_f32_e64 s[8:9], s52, v7
	s_nop 1
	v_cndmask_b32_e64 v7, v7, v18, s[8:9]
	v_rsq_f32_e32 v18, v7
	v_mad_i64_i32 v[6:7], s[4:5], v6, s53, v[124:125]
	v_lshl_add_u64 v[6:7], v[6:7], 0, v[116:117]
	v_mul_f32_e32 v19, 0x45800000, v18
	v_cndmask_b32_e64 v18, v18, v19, s[8:9]
	v_pk_mul_f32 v[16:17], v[16:17], v[18:19] op_sel_hi:[1,0]
	v_pk_mul_f32 v[8:9], v[8:9], v[18:19] op_sel_hi:[1,0]
	v_pk_mul_f32 v[12:13], v[12:13], v[18:19] op_sel_hi:[1,0]
	v_pk_mul_f32 v[10:11], v[10:11], v[18:19] op_sel_hi:[1,0]
	v_pk_mul_f32 v[0:1], v[0:1], v[18:19] op_sel_hi:[1,0]
	v_pk_mul_f32 v[14:15], v[14:15], v[18:19] op_sel_hi:[1,0]
	v_pk_mul_f32 v[4:5], v[4:5], v[18:19] op_sel_hi:[1,0]
	v_pk_mul_f32 v[2:3], v[2:3], v[18:19] op_sel_hi:[1,0]
	v_mul_f32_e32 v18, 0xbfb8aa3b, v17
	v_mul_f32_e32 v19, 0xbfb8aa3b, v9
	v_mul_f32_e32 v20, 0xbfb8aa3b, v13
	v_mul_f32_e32 v21, 0xbfb8aa3b, v11
	v_mul_f32_e32 v23, 0xbfb8aa3b, v1
	v_mul_f32_e32 v22, 0xbfb8aa3b, v15
	v_mul_f32_e32 v24, 0xbfb8aa3b, v5
	v_mul_f32_e32 v25, 0xbfb8aa3b, v3
	v_exp_f32_e32 v18, v18
	v_exp_f32_e32 v19, v19
	v_exp_f32_e32 v20, v20
	v_exp_f32_e32 v21, v21
	v_exp_f32_e32 v23, v23
	v_exp_f32_e32 v22, v22
	v_exp_f32_e32 v24, v24
	v_exp_f32_e32 v25, v25
	v_add_f32_e32 v18, 1.0, v18
	v_add_f32_e32 v19, 1.0, v19
	v_add_f32_e32 v20, 1.0, v20
	v_add_f32_e32 v21, 1.0, v21
	v_add_f32_e32 v23, 1.0, v23
	v_add_f32_e32 v22, 1.0, v22
	v_add_f32_e32 v24, 1.0, v24
	v_add_f32_e32 v25, 1.0, v25
	v_rcp_f32_e32 v18, v18
	v_rcp_f32_e32 v19, v19
	v_rcp_f32_e32 v20, v20
	v_rcp_f32_e32 v21, v21
	v_rcp_f32_e32 v23, v23
	v_rcp_f32_e32 v22, v22
	v_rcp_f32_e32 v24, v24
	v_rcp_f32_e32 v25, v25
	v_mul_f32_e32 v17, v17, v18
	v_mul_f32_e32 v9, v9, v19
	v_mul_f32_e32 v13, v13, v20
	v_mul_f32_e32 v11, v11, v21
	v_mul_f32_e32 v1, v1, v23
	v_mul_f32_e32 v15, v15, v22
	v_mul_f32_e32 v5, v5, v24
	v_mul_f32_e32 v3, v3, v25
	v_mul_f32_e32 v16, v16, v17
	v_mul_f32_e32 v8, v8, v9
	v_mul_f32_e32 v9, v12, v13
	v_mul_f32_e32 v10, v10, v11
	v_mul_f32_e32 v12, v0, v1
	v_cvt_pk_bf16_f32 v0, v16, v8
	v_cvt_pk_bf16_f32 v1, v9, v10
	s_mov_b64 s[4:5], -1
	v_mul_f32_e32 v11, v14, v15
	v_mul_f32_e32 v4, v4, v5
	v_mul_f32_e32 v2, v2, v3
	global_store_dwordx2 v[6:7], v[0:1], off
	v_cvt_pk_bf16_f32 v0, v11, v12
	v_cvt_pk_bf16_f32 v1, v4, v2
	global_store_dwordx2 v[6:7], v[0:1], off offset:128
	s_cbranch_vccnz .LBB0_346
	s_andn2_b64 vcc, exec, s[20:21]
	s_cbranch_vccnz .LBB0_345
	s_barrier
	s_branch .LBB0_345

; #define PG8_STAGE(bufoff, gbase, voff) do { _Pragma("unroll") for (int _i = 0; _i < 2; ++_i) \
;         __builtin_amdgcn_global_load_lds((const unsigned*)((const char*)(gbase) + (voff)[_i]), (PG8_LAS unsigned*)(lds + (bufoff) + ldsw + _i * 8192), 16, 0, 0); } while (0)
; #define PG8_WAIT_V(n) asm volatile("s_waitcnt vmcnt(" #n ")" ::: "memory")
; #define PG8_BAR __builtin_amdgcn_s_barrier()
; template <class Epi, class Sched, bool ALIGN_EPI = false, bool SP2 = false>
; __device__ __forceinline__ void gemm_phase(PG8_LAS unsigned char* lds, const Gemm g, const Sched& S, const Epi& E) {
;     ...
;     for (int i = 0; i < 2; ++i) { int R, C; stage_rc(tid * 16 + i * 8192, R, C); const int Rb = Epi::PERM ? ((R & ~31) + perm32(R & 31)) : R;
;         voffA[i] = (unsigned)(R * K + C) * 2u; voffB[i] = (unsigned)(Rb * K + C) * 2u; }
;     const size_t kstep = (size_t)(BK * 2);
;     const size_t hstep = (size_t)HALF * K * 2;
;     const size_t tstep = 2 * hstep;
;     const unsigned ldsw = (unsigned)wid * 1024u;
;     const int aoff = lds_byte(wr * 64 + fr, fq * 8), boff = lds_byte(wc * 32 + fr, fq * 8);
;     ...
;     Unit cur, nxt; int ui = 0;
;     if (!S.next(0, cur)) return;
;     f32x4 acc[2][2][4][2];
; #pragma unroll
;     for (int a = 0; a < 2; ++a)
; #pragma unroll
;         for (int b = 0; b < 2; ++b)
; #pragma unroll
;             for (int m = 0; m < 4; ++m)
; #pragma unroll
;                 for (int n = 0; n < 2; ++n) acc[a][b][m][n] = (f32x4){0.f, 0.f, 0.f, 0.f};
;     bf16x8 At[4][2], B0[2][2], B1[2][2];
;     const char* cA = (const char*)g.A + (size_t)cur.pm * tstep; const char* cB = (const char*)g.Bt + (size_t)cur.pn * tstep;
;     S.a_ready(cur);
;     if constexpr (SP2) {
;         PG8_STAGE(PG8_SB(0, 0), cB, voffB); PG8_STAGE(PG8_SB(0, 1), cB + hstep, voffB); PG8_STAGE(PG8_SA(0, 0), cA, voffA); PG8_STAGE(PG8_SA(0, 1), cA + hstep, voffA);
;         if (wr == 1) PG8_BAR;
;         PG8_WAIT_V(2); PG8_BAR;
;         PG8_STAGE(PG8_SB(1, 0), cB + kstep, voffB); PG8_STAGE(PG8_SA(1, 0), cA + kstep, voffA); PG8_STAGE(PG8_SB(1, 1), cB + hstep + kstep, voffB);
;         PG8_WAIT_V(6); PG8_BAR;
.LBB0_435:
	s_add_u32 s30, s10, 0xaa00000
	s_addc_u32 s31, s11, 0
	s_add_u32 s33, s10, 0x130400
	s_addc_u32 s44, s11, 0
	s_lshl_b32 s45, s8, 6
	s_lshl_b32 s13, s8, 13
	s_lshl_b32 s8, s9, 5
	s_mov_b64 s[20:21], 0x80
	s_and_b32 s46, s8, 0x60
	s_add_i32 m0, s25, 0x18000
	v_lshl_add_u64 v[6:7], v[6:7], 0, s[20:21]
	s_lshl_b32 s22, s46, 7
	s_waitcnt vmcnt(2)
	s_barrier
	global_load_lds_dwordx4 v[6:7], off
	v_lshl_add_u64 v[2:3], v[2:3], 0, s[20:21]
	s_add_i32 m0, s25, 0x1a000
	s_add_i32 s47, s25, 0x8000
	s_add_i32 s48, s25, 0xa000
	global_load_lds_dwordx4 v[2:3], off
	v_lshl_add_u64 v[0:1], v[0:1], 0, s[20:21]
	s_mov_b32 m0, s47
	s_add_u32 s8, s4, 0x160080
	global_load_lds_dwordx4 v[0:1], off
	v_lshl_add_u64 v[0:1], v[4:5], 0, s[20:21]
	s_mov_b32 m0, s48
	s_addc_u32 s9, s5, 0
	global_load_lds_dwordx4 v[0:1], off
	s_add_i32 m0, s25, 0x1c000
	v_lshl_add_u64 v[0:1], s[8:9], 0, v[130:131]
	global_load_lds_dwordx4 v[0:1], off
	v_lshl_add_u64 v[0:1], s[8:9], 0, v[134:135]
	s_add_i32 m0, s25, 0x1e000
	v_bfe_u32 v148, v8, 4, 2
	global_load_lds_dwordx4 v[0:1], off
	v_and_b32_e32 v149, 15, v8
	v_lshlrev_b32_e32 v0, 4, v148
	v_lshlrev_b32_e32 v1, 2, v8
	v_lshl_or_b32 v0, v149, 6, v0
	v_and_b32_e32 v1, 32, v1
	v_readlane_b32 s34, v244, 0
	v_bitop3_b32 v2, v0, s13, v1 bitop3:0xde
	v_bitop3_b32 v150, v0, s22, v1 bitop3:0xde
	s_cmpk_lt_u32 s6, 0x100
	v_readlane_b32 s35, v244, 1
	v_lshrrev_b32_e32 v1, 1, v9
	v_mul_lo_u32 v0, v10, s7
	s_cselect_b64 s[22:23], -1, 0
	s_ashr_i32 s49, s34, 31
	s_mov_b32 s50, s34
	v_mad_u64_u32 v[0:1], s[34:35], v1, s12, v[0:1]
	v_or_b32_e32 v0, v0, v11
	s_mov_b64 s[8:9], 0x160080
	v_add_lshl_u32 v0, v0, v12, 1
	v_mov_b32_e32 v1, v131
	v_lshl_add_u64 v[136:137], v[0:1], 0, s[8:9]
	v_lshrrev_b32_e32 v1, 1, v13
	v_mul_lo_u32 v0, v14, s7
	v_mad_u64_u32 v[0:1], s[6:7], v1, s12, v[0:1]
	s_waitcnt vmcnt(6)
	v_or_b32_e32 v0, v0, v15
	v_add_lshl_u32 v0, v0, v16, 1
	v_mov_b32_e32 v1, v131
	s_add_i32 s52, 0, 0x10000
	s_add_i32 s53, 0, 0x14000
	v_lshl_add_u64 v[138:139], v[0:1], 0, s[8:9]
	v_mov_b64_e32 v[140:141], 0x600
	v_mov_b64_e32 v[142:143], 0x5ff
	s_movk_i32 s51, 0xc1
	v_add_u32_e32 v151, s52, v150
	v_add_u32_e32 v153, s53, v150
	v_add_u32_e32 v154, 0, v2
	v_mbcnt_hi_u32_b32 v155, -1, v152
	s_barrier
	s_branch .LBB0_438
	s_nop 0
	s_nop 0
	s_nop 0
	s_nop 0
	s_nop 0
	s_nop 0
	s_nop 0

; __device__ __forceinline__ unsigned cvt_pk_bf16(float lo, float hi) { unsigned r; asm volatile("v_cvt_pk_bf16_f32 %0, %1, %2" : "=v"(r) : "v"(lo), "v"(hi)); return r; }
;     __device__ __forceinline__ void operator()(const f32x4 (&acc)[2][2][4][2], const Unit& u, int wr, int wc, int fr, int fq) const {
;         const int row0 = u.pm * BM + wr * 64 + fr; const int fcol0 = u.pn * 128 + wc * 16 + 4 * fq;
; #pragma unroll
;         for (int ai = 0; ai < 2; ++ai)
; #pragma unroll
;             for (int m = 0; m < 4; ++m) {
;                 const int row = row0 + ai * HALF + m * 16; const float rs = rsqrtf(sumsq[row] * inv_n + eps);
; #pragma unroll
;                 for (int bj = 0; bj < 2; ++bj) {
;                     const f32x4 g = acc[ai][bj][m][0] * rs, up = acc[ai][bj][m][1] * rs; f32x4 a;
; #pragma unroll
;                     for (int e = 0; e < 4; ++e) a[e] = g[e] * __builtin_amdgcn_rcpf(1.f + __builtin_amdgcn_exp2f(-1.4426950408889634f * g[e])) * up[e];
;                     u32x2 w; w.x = cvt_pk_bf16(a[0], a[1]); w.y = cvt_pk_bf16(a[2], a[3]);
;                     *(u32x2*)(O + (size_t)row * ldo + fcol0 + bj * 64) = w;
.LBB0_1052:
	v_lshl_add_u32 v144, s8, 8, v148
	v_ashrrev_i32_e32 v145, 31, v144
	v_lshl_add_u64 v[146:147], v[144:145], 2, s[16:17]
	global_load_dword v145, v[146:147], off
	global_load_dword v249, v[146:147], off offset:64
	global_load_dword v250, v[146:147], off offset:128
	global_load_dword v251, v[146:147], off offset:192
	global_load_dword v252, v[146:147], off offset:512
	global_load_dword v253, v[146:147], off offset:576
	global_load_dword v254, v[146:147], off offset:640
	global_load_dword v255, v[146:147], off offset:704
	v_lshl_or_b32 v156, s9, 7, v150
	v_mov_b32_e32 v158, v124
	v_mov_b32_e32 v159, v120
	v_mov_b32_e32 v120, v125
	v_mov_b32_e32 v160, v126
	v_mov_b32_e32 v161, v122
	v_mov_b32_e32 v122, v127
	v_mov_b32_e32 v126, v116
	v_mov_b32_e32 v127, v112
	v_mov_b32_e32 v112, v117
	v_or_b32_e32 v164, 16, v144
	v_mov_b32_e32 v162, v118
	v_mov_b32_e32 v163, v114
	v_mov_b32_e32 v114, v119
	v_ashrrev_i32_e32 v157, 31, v156
	v_ashrrev_i32_e32 v165, 31, v164
	v_lshlrev_b64 v[116:117], 1, v[156:157]
	v_lshl_add_u64 v[156:157], v[164:165], 2, s[16:17]
	v_mov_b64_e32 v[124:125], s[10:11]
	v_mad_i64_i32 v[118:119], s[4:5], v144, s51, v[124:125]
	v_lshl_add_u64 v[118:119], v[118:119], 0, v[116:117]
	s_waitcnt vmcnt(0)
	v_fmamk_f32 v145, v145, 0x3a000000, v154
	v_mul_f32_e32 v155, 0x4b800000, v145
	v_cmp_gt_f32_e32 vcc, s50, v145
	s_nop 1
	v_cndmask_b32_e32 v145, v145, v155, vcc
	v_rsq_f32_e32 v145, v145
	s_nop 0
	v_mul_f32_e32 v155, 0x45800000, v145
	v_cndmask_b32_e32 v166, v145, v155, vcc
	v_pk_mul_f32 v[158:159], v[158:159], v[166:167] op_sel_hi:[1,0]
	v_pk_mul_f32 v[120:121], v[120:121], v[166:167] op_sel_hi:[1,0]
	v_pk_mul_f32 v[160:161], v[160:161], v[166:167] op_sel_hi:[1,0]
	v_pk_mul_f32 v[122:123], v[122:123], v[166:167] op_sel_hi:[1,0]
	v_pk_mul_f32 v[126:127], v[126:127], v[166:167] op_sel_hi:[1,0]
	v_pk_mul_f32 v[112:113], v[112:113], v[166:167] op_sel_hi:[1,0]
	v_pk_mul_f32 v[162:163], v[162:163], v[166:167] op_sel_hi:[1,0]
	v_pk_mul_f32 v[114:115], v[114:115], v[166:167] op_sel_hi:[1,0]
	v_mul_f32_e32 v145, 0xbfb8aa3b, v159
	v_mul_f32_e32 v155, 0xbfb8aa3b, v121
	v_mul_f32_e32 v165, 0xbfb8aa3b, v161
	v_mul_f32_e32 v166, 0xbfb8aa3b, v123
	v_mul_f32_e32 v167, 0xbfb8aa3b, v127
	v_mul_f32_e32 v168, 0xbfb8aa3b, v113
	v_mul_f32_e32 v169, 0xbfb8aa3b, v163
	v_mul_f32_e32 v170, 0xbfb8aa3b, v115
	v_exp_f32_e32 v145, v145
	v_exp_f32_e32 v155, v155
	v_exp_f32_e32 v165, v165
	v_exp_f32_e32 v166, v166
	v_exp_f32_e32 v167, v167
	v_exp_f32_e32 v168, v168
	v_exp_f32_e32 v169, v169
	v_exp_f32_e32 v170, v170
	v_add_f32_e32 v145, 1.0, v145
	v_add_f32_e32 v155, 1.0, v155
	v_add_f32_e32 v165, 1.0, v165
	v_add_f32_e32 v166, 1.0, v166
	v_add_f32_e32 v167, 1.0, v167
	v_add_f32_e32 v168, 1.0, v168
	v_add_f32_e32 v169, 1.0, v169
	v_add_f32_e32 v170, 1.0, v170
	v_rcp_f32_e32 v145, v145
	v_rcp_f32_e32 v155, v155
	v_rcp_f32_e32 v165, v165
	v_rcp_f32_e32 v166, v166
	v_rcp_f32_e32 v167, v167
	v_rcp_f32_e32 v168, v168
	v_rcp_f32_e32 v169, v169
	v_rcp_f32_e32 v170, v170
	v_mul_f32_e32 v145, v159, v145
	v_mul_f32_e32 v121, v121, v155
	v_mul_f32_e32 v155, v161, v165
	v_mul_f32_e32 v123, v123, v166
	v_mul_f32_e32 v127, v127, v167
	v_mul_f32_e32 v113, v113, v168
	v_mul_f32_e32 v159, v163, v169
	v_mul_f32_e32 v115, v115, v170
	v_mul_f32_e32 v145, v158, v145
	v_mul_f32_e32 v120, v120, v121
	v_mul_f32_e32 v121, v160, v155
	v_mul_f32_e32 v122, v122, v123
	v_mul_f32_e32 v123, v126, v127
	v_mul_f32_e32 v126, v112, v113
	v_cvt_pk_bf16_f32 v112, v145, v120
	v_cvt_pk_bf16_f32 v113, v121, v122
	v_mul_f32_e32 v127, v162, v159
	v_mul_f32_e32 v114, v114, v115
	global_store_dwordx2 v[118:119], v[112:113], off
	v_cvt_pk_bf16_f32 v112, v123, v126
	v_cvt_pk_bf16_f32 v113, v127, v114
	global_store_dwordx2 v[118:119], v[112:113], off offset:128
	v_mov_b32_e32 v113, v104
	v_mov_b32_e32 v104, v109
	v_mov_b32_e32 v109, v106
	v_mov_b32_e32 v106, v111
	v_mov_b32_e32 v111, v96
	v_mov_b32_e32 v96, v101
	v_mov_b32_e32 v101, v98
	v_mov_b32_e32 v98, v103
	v_mov_b32_e32 v112, v108
	v_mov_b32_e32 v108, v110
	v_mov_b32_e32 v110, v100
	v_mov_b32_e32 v100, v102
	v_or_b32_e32 v102, 32, v144
	v_mad_i64_i32 v[114:115], s[4:5], v164, s51, v[124:125]
	v_lshl_add_u64 v[114:115], v[114:115], 0, v[116:117]
	v_mov_b32_e32 v118, v249
	v_fmamk_f32 v103, v118, 0x3a000000, v154
	v_mul_f32_e32 v118, 0x4b800000, v103
	v_cmp_gt_f32_e32 vcc, s50, v103
	s_nop 1
	v_cndmask_b32_e32 v103, v103, v118, vcc
	v_rsq_f32_e32 v120, v103
	v_ashrrev_i32_e32 v103, 31, v102
	v_lshl_add_u64 v[118:119], v[102:103], 2, s[16:17]
	v_mul_f32_e32 v103, 0x45800000, v120
	v_cndmask_b32_e32 v120, v120, v103, vcc
	v_pk_mul_f32 v[112:113], v[112:113], v[120:121] op_sel_hi:[1,0]
	v_pk_mul_f32 v[104:105], v[104:105], v[120:121] op_sel_hi:[1,0]
	v_pk_mul_f32 v[108:109], v[108:109], v[120:121] op_sel_hi:[1,0]
	v_pk_mul_f32 v[106:107], v[106:107], v[120:121] op_sel_hi:[1,0]
	v_pk_mul_f32 v[96:97], v[96:97], v[120:121] op_sel_hi:[1,0]
	v_pk_mul_f32 v[110:111], v[110:111], v[120:121] op_sel_hi:[1,0]
	v_pk_mul_f32 v[100:101], v[100:101], v[120:121] op_sel_hi:[1,0]
	v_pk_mul_f32 v[98:99], v[98:99], v[120:121] op_sel_hi:[1,0]
	v_mul_f32_e32 v103, 0xbfb8aa3b, v113
	v_mul_f32_e32 v120, 0xbfb8aa3b, v105
	v_mul_f32_e32 v121, 0xbfb8aa3b, v109
	v_mul_f32_e32 v122, 0xbfb8aa3b, v107
	v_mul_f32_e32 v126, 0xbfb8aa3b, v97
	v_mul_f32_e32 v123, 0xbfb8aa3b, v111
	v_mul_f32_e32 v127, 0xbfb8aa3b, v101
	v_mul_f32_e32 v145, 0xbfb8aa3b, v99
	v_exp_f32_e32 v103, v103
	v_exp_f32_e32 v120, v120
	v_exp_f32_e32 v121, v121
	v_exp_f32_e32 v122, v122
	v_exp_f32_e32 v126, v126
	v_exp_f32_e32 v123, v123
	v_exp_f32_e32 v127, v127
	v_exp_f32_e32 v145, v145
	v_add_f32_e32 v103, 1.0, v103
; __device__ __forceinline__ unsigned cvt_pk_bf16(float lo, float hi) { unsigned r; asm volatile("v_cvt_pk_bf16_f32 %0, %1, %2" : "=v"(r) : "v"(lo), "v"(hi)); return r; }
;     __device__ __forceinline__ void operator()(const f32x4 (&acc)[2][2][4][2], const Unit& u, int wr, int wc, int fr, int fq) const {
;     ...
;                 const int row = row0 + ai * HALF + m * 16; const float rs = rsqrtf(sumsq[row] * inv_n + eps);
; #pragma unroll
;                 for (int bj = 0; bj < 2; ++bj) {
;                     const f32x4 g = acc[ai][bj][m][0] * rs, up = acc[ai][bj][m][1] * rs; f32x4 a;
; #pragma unroll
;                     for (int e = 0; e < 4; ++e) a[e] = g[e] * __builtin_amdgcn_rcpf(1.f + __builtin_amdgcn_exp2f(-1.4426950408889634f * g[e])) * up[e];
;                     u32x2 w; w.x = cvt_pk_bf16(a[0], a[1]); w.y = cvt_pk_bf16(a[2], a[3]);
;                     *(u32x2*)(O + (size_t)row * ldo + fcol0 + bj * 64) = w;
	v_add_f32_e32 v120, 1.0, v120
	v_add_f32_e32 v121, 1.0, v121
	v_add_f32_e32 v122, 1.0, v122
	v_add_f32_e32 v126, 1.0, v126
	v_add_f32_e32 v123, 1.0, v123
	v_add_f32_e32 v127, 1.0, v127
	v_add_f32_e32 v145, 1.0, v145
	v_rcp_f32_e32 v103, v103
	v_rcp_f32_e32 v120, v120
	v_rcp_f32_e32 v121, v121
	v_rcp_f32_e32 v122, v122
	v_rcp_f32_e32 v126, v126
	v_rcp_f32_e32 v123, v123
	v_rcp_f32_e32 v127, v127
	v_rcp_f32_e32 v145, v145
	v_mul_f32_e32 v103, v113, v103
	v_mul_f32_e32 v105, v105, v120
	v_mul_f32_e32 v109, v109, v121
	v_mul_f32_e32 v107, v107, v122
	v_mul_f32_e32 v97, v97, v126
	v_mul_f32_e32 v111, v111, v123
	v_mul_f32_e32 v101, v101, v127
	v_mul_f32_e32 v99, v99, v145
	v_mul_f32_e32 v103, v112, v103
	v_mul_f32_e32 v104, v104, v105
	v_mul_f32_e32 v105, v108, v109
	v_mul_f32_e32 v106, v106, v107
	v_mul_f32_e32 v108, v96, v97
	v_cvt_pk_bf16_f32 v96, v103, v104
	v_cvt_pk_bf16_f32 v97, v105, v106
	v_mul_f32_e32 v107, v110, v111
	v_mul_f32_e32 v100, v100, v101
	v_mul_f32_e32 v98, v98, v99
	global_store_dwordx2 v[114:115], v[96:97], off
	v_cvt_pk_bf16_f32 v96, v107, v108
	v_cvt_pk_bf16_f32 v97, v100, v98
	global_store_dwordx2 v[114:115], v[96:97], off offset:128
	v_mov_b32_e32 v97, v88
	v_mov_b32_e32 v88, v93
	v_mov_b32_e32 v93, v90
	v_mov_b32_e32 v90, v95
	v_mov_b32_e32 v95, v80
	v_mov_b32_e32 v80, v85
	v_mov_b32_e32 v85, v82
	v_mov_b32_e32 v82, v87
	v_mad_i64_i32 v[98:99], s[4:5], v102, s51, v[124:125]
	v_mov_b32_e32 v96, v92
	v_mov_b32_e32 v92, v94
	v_mov_b32_e32 v94, v84
	v_mov_b32_e32 v84, v86
	v_or_b32_e32 v86, 48, v144
	v_lshl_add_u64 v[98:99], v[98:99], 0, v[116:117]
	v_mov_b32_e32 v100, v250
	v_fmamk_f32 v87, v100, 0x3a000000, v154
	v_mul_f32_e32 v100, 0x4b800000, v87
	v_cmp_gt_f32_e32 vcc, s50, v87
	s_nop 1
	v_cndmask_b32_e32 v87, v87, v100, vcc
	v_rsq_f32_e32 v102, v87
	v_ashrrev_i32_e32 v87, 31, v86
	v_lshl_add_u64 v[100:101], v[86:87], 2, s[16:17]
	v_mul_f32_e32 v87, 0x45800000, v102
	v_cndmask_b32_e32 v102, v102, v87, vcc
	v_pk_mul_f32 v[96:97], v[96:97], v[102:103] op_sel_hi:[1,0]
	v_pk_mul_f32 v[88:89], v[88:89], v[102:103] op_sel_hi:[1,0]
	v_pk_mul_f32 v[92:93], v[92:93], v[102:103] op_sel_hi:[1,0]
	v_pk_mul_f32 v[90:91], v[90:91], v[102:103] op_sel_hi:[1,0]
	v_pk_mul_f32 v[80:81], v[80:81], v[102:103] op_sel_hi:[1,0]
	v_pk_mul_f32 v[94:95], v[94:95], v[102:103] op_sel_hi:[1,0]
	v_pk_mul_f32 v[84:85], v[84:85], v[102:103] op_sel_hi:[1,0]
	v_pk_mul_f32 v[82:83], v[82:83], v[102:103] op_sel_hi:[1,0]
	v_mul_f32_e32 v87, 0xbfb8aa3b, v97
	v_mul_f32_e32 v102, 0xbfb8aa3b, v89
	v_mul_f32_e32 v103, 0xbfb8aa3b, v93
	v_mul_f32_e32 v104, 0xbfb8aa3b, v91
	v_mul_f32_e32 v106, 0xbfb8aa3b, v81
	v_mul_f32_e32 v105, 0xbfb8aa3b, v95
	v_mul_f32_e32 v107, 0xbfb8aa3b, v85
	v_mul_f32_e32 v108, 0xbfb8aa3b, v83
	v_exp_f32_e32 v87, v87
	v_exp_f32_e32 v102, v102
	v_exp_f32_e32 v103, v103
	v_exp_f32_e32 v104, v104
	v_exp_f32_e32 v106, v106
	v_exp_f32_e32 v105, v105
	v_exp_f32_e32 v107, v107
	v_exp_f32_e32 v108, v108
	v_add_f32_e32 v87, 1.0, v87
	v_add_f32_e32 v102, 1.0, v102
	v_add_f32_e32 v103, 1.0, v103
	v_add_f32_e32 v104, 1.0, v104
	v_add_f32_e32 v106, 1.0, v106
	v_add_f32_e32 v105, 1.0, v105
	v_add_f32_e32 v107, 1.0, v107
	v_add_f32_e32 v108, 1.0, v108
	v_rcp_f32_e32 v87, v87
	v_rcp_f32_e32 v102, v102
	v_rcp_f32_e32 v103, v103
	v_rcp_f32_e32 v104, v104
	v_rcp_f32_e32 v106, v106
	v_rcp_f32_e32 v105, v105
	v_rcp_f32_e32 v107, v107
	v_rcp_f32_e32 v108, v108
	v_mul_f32_e32 v87, v97, v87
	v_mul_f32_e32 v89, v89, v102
	v_mul_f32_e32 v93, v93, v103
	v_mul_f32_e32 v91, v91, v104
	v_mul_f32_e32 v81, v81, v106
	v_mul_f32_e32 v95, v95, v105
	v_mul_f32_e32 v85, v85, v107
	v_mul_f32_e32 v83, v83, v108
	v_mul_f32_e32 v87, v96, v87
	v_mul_f32_e32 v88, v88, v89
	v_mul_f32_e32 v89, v92, v93
	v_mul_f32_e32 v90, v90, v91
	v_mul_f32_e32 v92, v80, v81
	v_cvt_pk_bf16_f32 v80, v87, v88
	v_cvt_pk_bf16_f32 v81, v89, v90
	v_mul_f32_e32 v91, v94, v95
	v_mul_f32_e32 v84, v84, v85
	v_mul_f32_e32 v82, v82, v83
	global_store_dwordx2 v[98:99], v[80:81], off
	v_cvt_pk_bf16_f32 v80, v91, v92
	v_cvt_pk_bf16_f32 v81, v84, v82
	global_store_dwordx2 v[98:99], v[80:81], off offset:128
	v_mov_b32_e32 v80, v76
	v_mov_b32_e32 v76, v78
	v_mov_b32_e32 v78, v68
	v_mov_b32_e32 v68, v70
	v_mov_b32_e32 v81, v72
	v_mov_b32_e32 v72, v77
	v_mov_b32_e32 v77, v74
	v_mov_b32_e32 v74, v79
	v_mov_b32_e32 v79, v64
	v_mov_b32_e32 v64, v69
	v_mov_b32_e32 v69, v66
	v_mov_b32_e32 v66, v71
	v_mov_b32_e32 v82, v251
	v_fmamk_f32 v70, v82, 0x3a000000, v154
	v_mul_f32_e32 v71, 0x4b800000, v70
	v_cmp_gt_f32_e32 vcc, s50, v70
	s_nop 1
	v_cndmask_b32_e32 v70, v70, v71, vcc
	v_rsq_f32_e32 v82, v70
	v_mad_i64_i32 v[70:71], s[4:5], v86, s51, v[124:125]
	v_lshl_add_u64 v[70:71], v[70:71], 0, v[116:117]
	v_mul_f32_e32 v83, 0x45800000, v82
	v_cndmask_b32_e32 v82, v82, v83, vcc
	v_pk_mul_f32 v[80:81], v[80:81], v[82:83] op_sel_hi:[1,0]
	v_pk_mul_f32 v[72:73], v[72:73], v[82:83] op_sel_hi:[1,0]
	v_pk_mul_f32 v[76:77], v[76:77], v[82:83] op_sel_hi:[1,0]
	v_pk_mul_f32 v[74:75], v[74:75], v[82:83] op_sel_hi:[1,0]
	v_pk_mul_f32 v[64:65], v[64:65], v[82:83] op_sel_hi:[1,0]
	v_pk_mul_f32 v[78:79], v[78:79], v[82:83] op_sel_hi:[1,0]
	v_pk_mul_f32 v[68:69], v[68:69], v[82:83] op_sel_hi:[1,0]
	v_pk_mul_f32 v[66:67], v[66:67], v[82:83] op_sel_hi:[1,0]
	v_mul_f32_e32 v82, 0xbfb8aa3b, v81
	v_mul_f32_e32 v83, 0xbfb8aa3b, v73
	v_mul_f32_e32 v84, 0xbfb8aa3b, v77
	v_mul_f32_e32 v85, 0xbfb8aa3b, v75
	v_mul_f32_e32 v87, 0xbfb8aa3b, v65
	v_mul_f32_e32 v86, 0xbfb8aa3b, v79
	v_mul_f32_e32 v88, 0xbfb8aa3b, v69
	v_mul_f32_e32 v89, 0xbfb8aa3b, v67
	v_exp_f32_e32 v82, v82
	v_exp_f32_e32 v83, v83
	v_exp_f32_e32 v84, v84
	v_exp_f32_e32 v85, v85
; __device__ __forceinline__ unsigned cvt_pk_bf16(float lo, float hi) { unsigned r; asm volatile("v_cvt_pk_bf16_f32 %0, %1, %2" : "=v"(r) : "v"(lo), "v"(hi)); return r; }
;     __device__ __forceinline__ void operator()(const f32x4 (&acc)[2][2][4][2], const Unit& u, int wr, int wc, int fr, int fq) const {
;     ...
;                 const int row = row0 + ai * HALF + m * 16; const float rs = rsqrtf(sumsq[row] * inv_n + eps);
; #pragma unroll
;                 for (int bj = 0; bj < 2; ++bj) {
;                     const f32x4 g = acc[ai][bj][m][0] * rs, up = acc[ai][bj][m][1] * rs; f32x4 a;
; #pragma unroll
;                     for (int e = 0; e < 4; ++e) a[e] = g[e] * __builtin_amdgcn_rcpf(1.f + __builtin_amdgcn_exp2f(-1.4426950408889634f * g[e])) * up[e];
;                     u32x2 w; w.x = cvt_pk_bf16(a[0], a[1]); w.y = cvt_pk_bf16(a[2], a[3]);
;                     *(u32x2*)(O + (size_t)row * ldo + fcol0 + bj * 64) = w;
	v_exp_f32_e32 v87, v87
	v_exp_f32_e32 v86, v86
	v_exp_f32_e32 v88, v88
	v_exp_f32_e32 v89, v89
	v_add_f32_e32 v82, 1.0, v82
	v_add_f32_e32 v83, 1.0, v83
	v_add_f32_e32 v84, 1.0, v84
	v_add_f32_e32 v85, 1.0, v85
	v_add_f32_e32 v87, 1.0, v87
	v_add_f32_e32 v86, 1.0, v86
	v_add_f32_e32 v88, 1.0, v88
	v_add_f32_e32 v89, 1.0, v89
	v_rcp_f32_e32 v82, v82
	v_rcp_f32_e32 v83, v83
	v_rcp_f32_e32 v84, v84
	v_rcp_f32_e32 v85, v85
	v_rcp_f32_e32 v87, v87
	v_rcp_f32_e32 v86, v86
	v_rcp_f32_e32 v88, v88
	v_rcp_f32_e32 v89, v89
	v_mul_f32_e32 v81, v81, v82
	v_mul_f32_e32 v73, v73, v83
	v_mul_f32_e32 v77, v77, v84
	v_mul_f32_e32 v75, v75, v85
	v_mul_f32_e32 v65, v65, v87
	v_mul_f32_e32 v79, v79, v86
	v_mul_f32_e32 v69, v69, v88
	v_mul_f32_e32 v67, v67, v89
	v_mul_f32_e32 v80, v80, v81
	v_mul_f32_e32 v72, v72, v73
	v_mul_f32_e32 v73, v76, v77
	v_mul_f32_e32 v74, v74, v75
	v_mul_f32_e32 v76, v64, v65
	v_cvt_pk_bf16_f32 v64, v80, v72
	v_cvt_pk_bf16_f32 v65, v73, v74
	v_mul_f32_e32 v75, v78, v79
	v_mul_f32_e32 v68, v68, v69
	v_mul_f32_e32 v66, v66, v67
	global_store_dwordx2 v[70:71], v[64:65], off
	v_cvt_pk_bf16_f32 v64, v75, v76
	v_cvt_pk_bf16_f32 v65, v68, v66
	global_store_dwordx2 v[70:71], v[64:65], off offset:128
	v_mov_b32_e32 v65, v56
	v_mov_b32_e32 v56, v61
	v_mov_b32_e32 v61, v58
	v_mov_b32_e32 v58, v63
	v_mov_b32_e32 v63, v48
	v_mov_b32_e32 v48, v53
	v_mov_b32_e32 v53, v50
	v_mov_b32_e32 v50, v55
	v_mov_b32_e32 v64, v60
	v_mov_b32_e32 v60, v62
	v_mov_b32_e32 v62, v52
	v_mov_b32_e32 v52, v54
	v_add_u32_e32 v54, 0x80, v144
	v_mov_b32_e32 v66, v252
	v_fmamk_f32 v55, v66, 0x3a000000, v154
	v_mul_f32_e32 v66, 0x4b800000, v55
	v_cmp_gt_f32_e32 vcc, s50, v55
	s_nop 1
	v_cndmask_b32_e32 v55, v55, v66, vcc
	v_rsq_f32_e32 v66, v55
	v_mad_i64_i32 v[54:55], s[4:5], v54, s51, v[124:125]
	v_lshl_add_u64 v[54:55], v[54:55], 0, v[116:117]
	v_mul_f32_e32 v67, 0x45800000, v66
	v_cndmask_b32_e32 v66, v66, v67, vcc
	v_pk_mul_f32 v[64:65], v[64:65], v[66:67] op_sel_hi:[1,0]
	v_pk_mul_f32 v[56:57], v[56:57], v[66:67] op_sel_hi:[1,0]
	v_pk_mul_f32 v[60:61], v[60:61], v[66:67] op_sel_hi:[1,0]
	v_pk_mul_f32 v[58:59], v[58:59], v[66:67] op_sel_hi:[1,0]
	v_pk_mul_f32 v[48:49], v[48:49], v[66:67] op_sel_hi:[1,0]
	v_pk_mul_f32 v[62:63], v[62:63], v[66:67] op_sel_hi:[1,0]
	v_pk_mul_f32 v[52:53], v[52:53], v[66:67] op_sel_hi:[1,0]
	v_pk_mul_f32 v[50:51], v[50:51], v[66:67] op_sel_hi:[1,0]
	v_mul_f32_e32 v66, 0xbfb8aa3b, v65
	v_mul_f32_e32 v67, 0xbfb8aa3b, v57
	v_mul_f32_e32 v68, 0xbfb8aa3b, v61
	v_mul_f32_e32 v69, 0xbfb8aa3b, v59
	v_mul_f32_e32 v71, 0xbfb8aa3b, v49
	v_mul_f32_e32 v70, 0xbfb8aa3b, v63
	v_mul_f32_e32 v72, 0xbfb8aa3b, v53
	v_mul_f32_e32 v73, 0xbfb8aa3b, v51
	v_exp_f32_e32 v66, v66
	v_exp_f32_e32 v67, v67
	v_exp_f32_e32 v68, v68
	v_exp_f32_e32 v69, v69
	v_exp_f32_e32 v71, v71
	v_exp_f32_e32 v70, v70
	v_exp_f32_e32 v72, v72
	v_exp_f32_e32 v73, v73
	v_add_f32_e32 v66, 1.0, v66
	v_add_f32_e32 v67, 1.0, v67
	v_add_f32_e32 v68, 1.0, v68
	v_add_f32_e32 v69, 1.0, v69
	v_add_f32_e32 v71, 1.0, v71
	v_add_f32_e32 v70, 1.0, v70
	v_add_f32_e32 v72, 1.0, v72
	v_add_f32_e32 v73, 1.0, v73
	v_rcp_f32_e32 v66, v66
	v_rcp_f32_e32 v67, v67
	v_rcp_f32_e32 v68, v68
	v_rcp_f32_e32 v69, v69
	v_rcp_f32_e32 v71, v71
	v_rcp_f32_e32 v70, v70
	v_rcp_f32_e32 v72, v72
	v_rcp_f32_e32 v73, v73
	v_mul_f32_e32 v65, v65, v66
	v_mul_f32_e32 v57, v57, v67
	v_mul_f32_e32 v61, v61, v68
	v_mul_f32_e32 v59, v59, v69
	v_mul_f32_e32 v49, v49, v71
	v_mul_f32_e32 v63, v63, v70
	v_mul_f32_e32 v53, v53, v72
	v_mul_f32_e32 v51, v51, v73
	v_mul_f32_e32 v64, v64, v65
	v_mul_f32_e32 v56, v56, v57
	v_mul_f32_e32 v57, v60, v61
	v_mul_f32_e32 v58, v58, v59
	v_mul_f32_e32 v60, v48, v49
	v_cvt_pk_bf16_f32 v48, v64, v56
	v_cvt_pk_bf16_f32 v49, v57, v58
	v_mul_f32_e32 v59, v62, v63
	v_mul_f32_e32 v52, v52, v53
	v_mul_f32_e32 v50, v50, v51
	global_store_dwordx2 v[54:55], v[48:49], off
	v_cvt_pk_bf16_f32 v48, v59, v60
	v_cvt_pk_bf16_f32 v49, v52, v50
	global_store_dwordx2 v[54:55], v[48:49], off offset:128
	v_mov_b32_e32 v49, v40
	v_mov_b32_e32 v40, v45
	v_mov_b32_e32 v45, v42
	v_mov_b32_e32 v42, v47
	v_mov_b32_e32 v47, v32
	v_mov_b32_e32 v32, v37
	v_mov_b32_e32 v37, v34
	v_mov_b32_e32 v34, v39
	v_mov_b32_e32 v48, v44
	v_mov_b32_e32 v44, v46
	v_mov_b32_e32 v46, v36
	v_mov_b32_e32 v36, v38
	v_add_u32_e32 v38, 0x90, v144
	v_mov_b32_e32 v50, v253
	v_fmamk_f32 v39, v50, 0x3a000000, v154
	v_mul_f32_e32 v50, 0x4b800000, v39
	v_cmp_gt_f32_e32 vcc, s50, v39
	s_nop 1
	v_cndmask_b32_e32 v39, v39, v50, vcc
	v_rsq_f32_e32 v50, v39
	v_mad_i64_i32 v[38:39], s[4:5], v38, s51, v[124:125]
	v_lshl_add_u64 v[38:39], v[38:39], 0, v[116:117]
	v_mul_f32_e32 v51, 0x45800000, v50
	v_cndmask_b32_e32 v50, v50, v51, vcc
	v_pk_mul_f32 v[48:49], v[48:49], v[50:51] op_sel_hi:[1,0]
	v_pk_mul_f32 v[40:41], v[40:41], v[50:51] op_sel_hi:[1,0]
	v_pk_mul_f32 v[44:45], v[44:45], v[50:51] op_sel_hi:[1,0]
	v_pk_mul_f32 v[42:43], v[42:43], v[50:51] op_sel_hi:[1,0]
	v_pk_mul_f32 v[32:33], v[32:33], v[50:51] op_sel_hi:[1,0]
	v_pk_mul_f32 v[46:47], v[46:47], v[50:51] op_sel_hi:[1,0]
	v_pk_mul_f32 v[36:37], v[36:37], v[50:51] op_sel_hi:[1,0]
	v_pk_mul_f32 v[34:35], v[34:35], v[50:51] op_sel_hi:[1,0]
	v_mul_f32_e32 v50, 0xbfb8aa3b, v49
	v_mul_f32_e32 v51, 0xbfb8aa3b, v41
	v_mul_f32_e32 v52, 0xbfb8aa3b, v45
	v_mul_f32_e32 v53, 0xbfb8aa3b, v43
	v_mul_f32_e32 v55, 0xbfb8aa3b, v33
	v_mul_f32_e32 v54, 0xbfb8aa3b, v47
	v_mul_f32_e32 v56, 0xbfb8aa3b, v37
	v_mul_f32_e32 v57, 0xbfb8aa3b, v35
	v_exp_f32_e32 v50, v50
	v_exp_f32_e32 v51, v51
	v_exp_f32_e32 v52, v52
	v_exp_f32_e32 v53, v53
	v_exp_f32_e32 v55, v55
	v_exp_f32_e32 v54, v54
	v_exp_f32_e32 v56, v56
	v_exp_f32_e32 v57, v57
; __device__ __forceinline__ unsigned cvt_pk_bf16(float lo, float hi) { unsigned r; asm volatile("v_cvt_pk_bf16_f32 %0, %1, %2" : "=v"(r) : "v"(lo), "v"(hi)); return r; }
; #define PG8_BAR __builtin_amdgcn_s_barrier()
;     __device__ __forceinline__ void operator()(const f32x4 (&acc)[2][2][4][2], const Unit& u, int wr, int wc, int fr, int fq) const {
;     ...
;                 const int row = row0 + ai * HALF + m * 16; const float rs = rsqrtf(sumsq[row] * inv_n + eps);
; #pragma unroll
;                 for (int bj = 0; bj < 2; ++bj) {
;                     const f32x4 g = acc[ai][bj][m][0] * rs, up = acc[ai][bj][m][1] * rs; f32x4 a;
; #pragma unroll
;                     for (int e = 0; e < 4; ++e) a[e] = g[e] * __builtin_amdgcn_rcpf(1.f + __builtin_amdgcn_exp2f(-1.4426950408889634f * g[e])) * up[e];
;                     u32x2 w; w.x = cvt_pk_bf16(a[0], a[1]); w.y = cvt_pk_bf16(a[2], a[3]);
;                     *(u32x2*)(O + (size_t)row * ldo + fcol0 + bj * 64) = w;
; template <class Epi, class Sched, bool ALIGN_EPI = false, bool SP2 = false>
; __device__ __forceinline__ void gemm_phase(PG8_LAS unsigned char* lds, const Gemm g, const Sched& S, const Epi& E) {
;     ...
;         if constexpr (ALIGN_EPI) { if (wr == 0) PG8_BAR; }
;         if constexpr (!Epi::AFTER_DRAIN) { E(acc, cur, wr, wc, fr, fq); S.done(cur); }
;         if (!has_next) break;
; #pragma unroll
;         for (int a = 0; a < 2; ++a)
; #pragma unroll
;             for (int b = 0; b < 2; ++b)
; #pragma unroll
;                 for (int m = 0; m < 4; ++m)
; #pragma unroll
;                     for (int n = 0; n < 2; ++n) acc[a][b][m][n] = (f32x4){0.f, 0.f, 0.f, 0.f};
;         cur = nxt; cA = nA; cB = nB; ++ui;
;         if constexpr (ALIGN_EPI) { if (wr == 1) PG8_BAR; }
	v_add_f32_e32 v50, 1.0, v50
	v_add_f32_e32 v51, 1.0, v51
	v_add_f32_e32 v52, 1.0, v52
	v_add_f32_e32 v53, 1.0, v53
	v_add_f32_e32 v55, 1.0, v55
	v_add_f32_e32 v54, 1.0, v54
	v_add_f32_e32 v56, 1.0, v56
	v_add_f32_e32 v57, 1.0, v57
	v_rcp_f32_e32 v50, v50
	v_rcp_f32_e32 v51, v51
	v_rcp_f32_e32 v52, v52
	v_rcp_f32_e32 v53, v53
	v_rcp_f32_e32 v55, v55
	v_rcp_f32_e32 v54, v54
	v_rcp_f32_e32 v56, v56
	v_rcp_f32_e32 v57, v57
	v_mul_f32_e32 v49, v49, v50
	v_mul_f32_e32 v41, v41, v51
	v_mul_f32_e32 v45, v45, v52
	v_mul_f32_e32 v43, v43, v53
	v_mul_f32_e32 v33, v33, v55
	v_mul_f32_e32 v47, v47, v54
	v_mul_f32_e32 v37, v37, v56
	v_mul_f32_e32 v35, v35, v57
	v_mul_f32_e32 v48, v48, v49
	v_mul_f32_e32 v40, v40, v41
	v_mul_f32_e32 v41, v44, v45
	v_mul_f32_e32 v42, v42, v43
	v_mul_f32_e32 v44, v32, v33
	v_cvt_pk_bf16_f32 v32, v48, v40
	v_cvt_pk_bf16_f32 v33, v41, v42
	v_mul_f32_e32 v43, v46, v47
	v_mul_f32_e32 v36, v36, v37
	v_mul_f32_e32 v34, v34, v35
	global_store_dwordx2 v[38:39], v[32:33], off
	v_cvt_pk_bf16_f32 v32, v43, v44
	v_cvt_pk_bf16_f32 v33, v36, v34
	global_store_dwordx2 v[38:39], v[32:33], off offset:128
	v_mov_b32_e32 v33, v24
	v_mov_b32_e32 v24, v29
	v_mov_b32_e32 v29, v26
	v_mov_b32_e32 v26, v31
	v_mov_b32_e32 v31, v16
	v_mov_b32_e32 v16, v21
	v_mov_b32_e32 v21, v18
	v_mov_b32_e32 v18, v23
	v_mov_b32_e32 v32, v28
	v_mov_b32_e32 v28, v30
	v_mov_b32_e32 v30, v20
	v_mov_b32_e32 v20, v22
	v_add_u32_e32 v22, 0xa0, v144
	v_mov_b32_e32 v34, v254
	v_fmamk_f32 v23, v34, 0x3a000000, v154
	v_mul_f32_e32 v34, 0x4b800000, v23
	v_cmp_gt_f32_e32 vcc, s50, v23
	s_nop 1
	v_cndmask_b32_e32 v23, v23, v34, vcc
	v_rsq_f32_e32 v34, v23
	v_mad_i64_i32 v[22:23], s[4:5], v22, s51, v[124:125]
	v_lshl_add_u64 v[22:23], v[22:23], 0, v[116:117]
	v_mul_f32_e32 v35, 0x45800000, v34
	v_cndmask_b32_e32 v34, v34, v35, vcc
	v_pk_mul_f32 v[32:33], v[32:33], v[34:35] op_sel_hi:[1,0]
	v_pk_mul_f32 v[24:25], v[24:25], v[34:35] op_sel_hi:[1,0]
	v_pk_mul_f32 v[28:29], v[28:29], v[34:35] op_sel_hi:[1,0]
	v_pk_mul_f32 v[26:27], v[26:27], v[34:35] op_sel_hi:[1,0]
	v_pk_mul_f32 v[16:17], v[16:17], v[34:35] op_sel_hi:[1,0]
	v_pk_mul_f32 v[30:31], v[30:31], v[34:35] op_sel_hi:[1,0]
	v_pk_mul_f32 v[20:21], v[20:21], v[34:35] op_sel_hi:[1,0]
	v_pk_mul_f32 v[18:19], v[18:19], v[34:35] op_sel_hi:[1,0]
	v_mul_f32_e32 v34, 0xbfb8aa3b, v33
	v_mul_f32_e32 v35, 0xbfb8aa3b, v25
	v_mul_f32_e32 v36, 0xbfb8aa3b, v29
	v_mul_f32_e32 v37, 0xbfb8aa3b, v27
	v_mul_f32_e32 v39, 0xbfb8aa3b, v17
	v_mul_f32_e32 v38, 0xbfb8aa3b, v31
	v_mul_f32_e32 v40, 0xbfb8aa3b, v21
	v_mul_f32_e32 v41, 0xbfb8aa3b, v19
	v_exp_f32_e32 v34, v34
	v_exp_f32_e32 v35, v35
	v_exp_f32_e32 v36, v36
	v_exp_f32_e32 v37, v37
	v_exp_f32_e32 v39, v39
	v_exp_f32_e32 v38, v38
	v_exp_f32_e32 v40, v40
	v_exp_f32_e32 v41, v41
	v_add_f32_e32 v34, 1.0, v34
	v_add_f32_e32 v35, 1.0, v35
	v_add_f32_e32 v36, 1.0, v36
	v_add_f32_e32 v37, 1.0, v37
	v_add_f32_e32 v39, 1.0, v39
	v_add_f32_e32 v38, 1.0, v38
	v_add_f32_e32 v40, 1.0, v40
	v_add_f32_e32 v41, 1.0, v41
	v_rcp_f32_e32 v34, v34
	v_rcp_f32_e32 v35, v35
	v_rcp_f32_e32 v36, v36
	v_rcp_f32_e32 v37, v37
	v_rcp_f32_e32 v39, v39
	v_rcp_f32_e32 v38, v38
	v_rcp_f32_e32 v40, v40
	v_rcp_f32_e32 v41, v41
	v_mul_f32_e32 v33, v33, v34
	v_mul_f32_e32 v25, v25, v35
	v_mul_f32_e32 v29, v29, v36
	v_mul_f32_e32 v27, v27, v37
	v_mul_f32_e32 v17, v17, v39
	v_mul_f32_e32 v31, v31, v38
	v_mul_f32_e32 v21, v21, v40
	v_mul_f32_e32 v19, v19, v41
	v_mul_f32_e32 v32, v32, v33
	v_mul_f32_e32 v24, v24, v25
	v_mul_f32_e32 v25, v28, v29
	v_mul_f32_e32 v26, v26, v27
	v_mul_f32_e32 v28, v16, v17
	v_cvt_pk_bf16_f32 v16, v32, v24
	v_cvt_pk_bf16_f32 v17, v25, v26
	v_mul_f32_e32 v27, v30, v31
	v_mul_f32_e32 v20, v20, v21
	v_mul_f32_e32 v18, v18, v19
	global_store_dwordx2 v[22:23], v[16:17], off
	v_cvt_pk_bf16_f32 v16, v27, v28
	v_cvt_pk_bf16_f32 v17, v20, v18
	global_store_dwordx2 v[22:23], v[16:17], off offset:128
	v_mov_b32_e32 v17, v8
	v_mov_b32_e32 v8, v13
	v_mov_b32_e32 v13, v10
	v_mov_b32_e32 v10, v15
	v_mov_b32_e32 v15, v0
	v_mov_b32_e32 v0, v5
	v_mov_b32_e32 v5, v2
	v_mov_b32_e32 v2, v7
	v_mov_b32_e32 v16, v12
	v_mov_b32_e32 v12, v14
	v_mov_b32_e32 v14, v4
	v_mov_b32_e32 v4, v6
	v_add_u32_e32 v6, 0xb0, v144
	s_andn2_b64 vcc, exec, s[6:7]
	v_mov_b32_e32 v18, v255
	v_fmamk_f32 v7, v18, 0x3a000000, v154
	v_mul_f32_e32 v18, 0x4b800000, v7
	v_cmp_gt_f32_e64 s[8:9], s50, v7
	s_nop 1
	v_cndmask_b32_e64 v7, v7, v18, s[8:9]
	v_rsq_f32_e32 v18, v7
	v_mad_i64_i32 v[6:7], s[4:5], v6, s51, v[124:125]
	v_lshl_add_u64 v[6:7], v[6:7], 0, v[116:117]
	v_mul_f32_e32 v19, 0x45800000, v18
	v_cndmask_b32_e64 v18, v18, v19, s[8:9]
	v_pk_mul_f32 v[16:17], v[16:17], v[18:19] op_sel_hi:[1,0]
	v_pk_mul_f32 v[8:9], v[8:9], v[18:19] op_sel_hi:[1,0]
	v_pk_mul_f32 v[12:13], v[12:13], v[18:19] op_sel_hi:[1,0]
	v_pk_mul_f32 v[10:11], v[10:11], v[18:19] op_sel_hi:[1,0]
	v_pk_mul_f32 v[0:1], v[0:1], v[18:19] op_sel_hi:[1,0]
	v_pk_mul_f32 v[14:15], v[14:15], v[18:19] op_sel_hi:[1,0]
	v_pk_mul_f32 v[4:5], v[4:5], v[18:19] op_sel_hi:[1,0]
	v_pk_mul_f32 v[2:3], v[2:3], v[18:19] op_sel_hi:[1,0]
	v_mul_f32_e32 v18, 0xbfb8aa3b, v17
	v_mul_f32_e32 v19, 0xbfb8aa3b, v9
	v_mul_f32_e32 v20, 0xbfb8aa3b, v13
	v_mul_f32_e32 v21, 0xbfb8aa3b, v11
	v_mul_f32_e32 v23, 0xbfb8aa3b, v1
	v_mul_f32_e32 v22, 0xbfb8aa3b, v15
	v_mul_f32_e32 v24, 0xbfb8aa3b, v5
	v_mul_f32_e32 v25, 0xbfb8aa3b, v3
	v_exp_f32_e32 v18, v18
	v_exp_f32_e32 v19, v19
	v_exp_f32_e32 v20, v20
	v_exp_f32_e32 v21, v21
	v_exp_f32_e32 v23, v23
	v_exp_f32_e32 v22, v22
	v_exp_f32_e32 v24, v24
	v_exp_f32_e32 v25, v25
	v_add_f32_e32 v18, 1.0, v18
	v_add_f32_e32 v19, 1.0, v19
	v_add_f32_e32 v20, 1.0, v20
	v_add_f32_e32 v21, 1.0, v21
	v_add_f32_e32 v23, 1.0, v23
	v_add_f32_e32 v22, 1.0, v22
	v_add_f32_e32 v24, 1.0, v24
	v_add_f32_e32 v25, 1.0, v25
	v_rcp_f32_e32 v18, v18
	v_rcp_f32_e32 v19, v19
	v_rcp_f32_e32 v20, v20
	v_rcp_f32_e32 v21, v21
	v_rcp_f32_e32 v23, v23
	v_rcp_f32_e32 v22, v22
	v_rcp_f32_e32 v24, v24
	v_rcp_f32_e32 v25, v25
	v_mul_f32_e32 v17, v17, v18
	v_mul_f32_e32 v9, v9, v19
	v_mul_f32_e32 v13, v13, v20
	v_mul_f32_e32 v11, v11, v21
	v_mul_f32_e32 v1, v1, v23
	v_mul_f32_e32 v15, v15, v22
	v_mul_f32_e32 v5, v5, v24
	v_mul_f32_e32 v3, v3, v25
	v_mul_f32_e32 v16, v16, v17
	v_mul_f32_e32 v8, v8, v9
	v_mul_f32_e32 v9, v12, v13
	v_mul_f32_e32 v10, v10, v11
	v_mul_f32_e32 v12, v0, v1
	v_cvt_pk_bf16_f32 v0, v16, v8
	v_cvt_pk_bf16_f32 v1, v9, v10
	s_mov_b64 s[4:5], -1
	v_mul_f32_e32 v11, v14, v15
	v_mul_f32_e32 v4, v4, v5
	v_mul_f32_e32 v2, v2, v3
	global_store_dwordx2 v[6:7], v[0:1], off
	v_cvt_pk_bf16_f32 v0, v11, v12
	v_cvt_pk_bf16_f32 v1, v4, v2
	global_store_dwordx2 v[6:7], v[0:1], off offset:128
	s_cbranch_vccnz .LBB0_1045
	s_andn2_b64 vcc, exec, s[18:19]
	s_cbranch_vccnz .LBB0_1044
	s_barrier
	s_branch .LBB0_1044
